# x17: Q pre-scaled by scale*log2e in registers; running max folded into QK accumulator init (SrcC=-m), no per-element scale/shift fma; rare-path rescale out of line
# speedup vs baseline: 1.0406x; 1.0388x over previous
; template <int DQK> __device__ __forceinline__ void partialSM(f32x16& p0, f32x16& p1, float& m_reg, float& mn, float& alpha) {
;     ...
;   if (__builtin_expect(__all(pmax - m_reg <= THR / SCALE), 1)) { mn = m_reg; alpha = 1.f; }
; __device__ __forceinline__ void run_phase(Ctx& F0, const int p) {
;     ...
;         if (!last) for (int u = F.vcu; u < 16; u += F.G) {
;             const int b = u >> 2, h = u & 3;
;             att::attn_unit<96, 0, 384, 384, 256>(Qb + (size_t)(ML + b * CTXL) * 384 + h * 96, Kb + h * 96, Vb + h * 64,
;                                   ML + b * CTXL, 4, 0, 4, Ob + (size_t)(ML + b * CTXL) * DM + h * 64, F.lds, 0, 0, 0);
;         }
.LBB0_296:
	s_mov_b32 s80, 0x429cc470
	v_readlane_b32 s0, v255, 35
	s_cmp_gt_i32 s0, 15
	v_readlane_b32 s4, v255, 40
	s_cselect_b64 s[0:1], -1, 0
	v_readlane_b32 s5, v255, 41
	s_or_b64 s[0:1], s[4:5], s[0:1]
	s_and_b64 vcc, exec, s[0:1]
	s_cbranch_vccnz .LBB0_333
	v_readlane_b32 s24, v255, 35
	s_lshl_b32 s22, s24, 6
	s_lshl_b32 s23, s89, 6
	s_branch .LBB0_319

; __device__ __forceinline__ int fresh_tid() { int t = threadIdx.x; asm volatile("" : "+v"(t)); return t; }
; __device__ __forceinline__ int v_st(int k, int c) { const int kk = (k & ~0xC) | ((k & 4) << 1) | ((k & 8) >> 1); return ((kk >> 3) * 4 + (c >> 5)) * 512 + ((kk & 7) * 32 + (c & 31)) * 2; }
; __device__ __forceinline__ int v_rd_base(int lane) { return ((lane & 3) << 3) | (((lane >> 2) & 3) << 6) | (((lane >> 4) & 1) << 5) | (((lane >> 5) & 1) << 8); }
; #define SLOAD(i, j) do { const long kr_ = KROW(j); sr_[i].vs0 = ld8(Vp + (kr_ + sr) * ldv + sc); sr_[i].ks0 = ld8(Kp + (kr_ + sr) * ldk + sc); \
;     if (DQK == 96) sr_[i].ks1 = ld8(Kp + (kr_ + sr2) * ldk + sc2); } while (0)
; #define SWRITE(b, i) do { *(bf16x8*)(V_lds + (b) * SHM_V + vst0) = sr_[i].vs0; *(bf16x8*)(K_lds + (b) * SHM_K + kst0) = sr_[i].ks0; \
;     if (DQK == 96) *(bf16x8*)(K_lds + (b) * SHM_K + kst1) = sr_[i].ks1; } while (0)
; template <int DQK, int MODE, int ldq, int ldk, int ldv> ...
;     ...
;   const int tid = fresh_tid(), wid = tid >> 6, lane = tid & 63, r32 = lane & 31, hi = lane >> 5;
;   char* V_lds = lds; char* K_lds = lds + 2 * SHM_V;
;   float* ws = (float*)(lds + 2 * SHM_V + 2 * SHM_K) + wid * 64; float* li_l = ws; float* al_l = ws + 32;
;   float m_reg = -1e30f, l_reg = 0; f32x16 o[2] = {}; bf16x8 qr[DQK / 16];
;   const bf16_t* Qw = Qb + (long)(wid * QBLK + r32) * ldq + hi * 8;
; #pragma unroll
;   for (int d0 = 0; d0 < DQK / 16; ++d0) qr[d0] = ld8(Qw + d0 * 16);
;   NaInfo na; na.brow = (const float*)(lds + rpb_off); na.qr = r0 + (wid >> 1); na.qc = (wid & 1) * 32 + r32;
;   const int sr = tid >> 3, sc = (tid & 7) * 8, vst0 = v_st(sr, sc), kst0 = KSWZ(sr, sc * 2);
;   const int sr2 = (tid & 255) >> 2, sc2 = 64 + (tid & 3) * 8, kst1 = KSWZ(sr2, sc2 * 2);
;   const int vb0 = (int)(uintptr_t)V_lds + v_rd_base(lane);
;   struct { bf16x8 vs0, ks0, ks1; } sr_[2];
;     ...
;   f32x16 pA0, pA1, pB0, pB1; float mnA, mnB, alA, alB; bf16x8 pa0, pa1, pa2, pa3;
;   constexpr int SE = 0, SO = 1;
;   SLOAD(SE, 0); SLOAD(SO, 1); asm volatile("s_waitcnt vmcnt(0)" ::: "memory"); SWRITE(0, SE); SWRITE(1, SO);
.LBB0_299:
	v_readfirstlane_b32 s32, v234
	s_nop 0
	s_lshr_b32 s32, s32, 8
	s_ashr_i32 s11, s22, 7
	s_lshl_b32 s0, s22, 8
	s_lshl_b32 s10, s11, 13
	s_and_b32 s0, s0, 0x1f00
	s_or_b32 s6, s10, s0
	s_bfe_u32 s4, s22, 0x20005
	s_ashr_i32 s7, s6, 31
	s_mul_i32 s1, s6, 0x300
	s_mul_hi_i32 s0, s6, 0x300
	s_add_u32 s1, s16, s1
	s_addc_u32 s0, s17, s0
	s_mul_i32 s5, s4, 0xc0
	s_add_u32 s12, s1, s5
	s_addc_u32 s13, s0, 0
	s_add_u32 s0, s18, s5
	s_addc_u32 s1, s19, 0
	s_lshl_b32 s23, s4, 6
	s_lshl_b32 s4, s4, 7
	s_add_u32 s4, s20, s4
	s_addc_u32 s5, s21, 0
	s_lshl_b32 s24, s11, 8
	s_add_i32 s24, s24, 0x8000
	v_mov_b32_e32 v52, v234
	s_add_i32 s26, 0, 0x10000
	s_cmp_lg_u32 0, -1
	v_ashrrev_i32_e32 v130, 3, v52
	v_lshlrev_b32_e32 v28, 3, v52
	v_and_b32_e32 v0, 56, v28
	v_bfe_u32 v132, v52, 2, 6
	s_cselect_b32 s25, 0, 0
	s_ashr_i32 s11, s10, 31
	v_ashrrev_i32_e32 v131, 31, v130
	s_waitcnt lgkmcnt(0)
	v_lshlrev_b32_e32 v48, 1, v0
	v_lshl_add_u64 v[0:1], v[130:131], 0, s[10:11]
	v_mov_b64_e32 v[24:25], s[0:1]
	v_or_b32_e32 v8, s10, v132
	v_mad_u64_u32 v[4:5], s[28:29], v0, s70, v[24:25]
	v_mad_i64_i32 v[8:9], s[28:29], v8, s70, v[24:25]
	s_or_b32 s28, s10, 64
	s_ashr_i32 s29, s28, 31
	v_lshl_add_u64 v[16:17], v[130:131], 0, s[28:29]
	v_lshlrev_b64 v[2:3], 9, v[0:1]
	v_mad_u64_u32 v[18:19], s[30:31], v16, s70, v[24:25]
	v_lshl_add_u64 v[2:3], s[4:5], 0, v[2:3]
	v_mov_b32_e32 v49, v205
	v_mad_i32_i24 v5, v1, s70, v5
	v_mad_i32_i24 v19, v17, s70, v19
	v_lshlrev_b32_e32 v53, 4, v52
	v_lshl_add_u64 v[2:3], v[2:3], 0, v[48:49]
	v_lshl_add_u64 v[4:5], v[4:5], 0, v[48:49]
	v_lshlrev_b64 v[10:11], 9, v[16:17]
	v_lshl_add_u64 v[16:17], v[18:19], 0, v[48:49]
	v_or_b32_e32 v18, s28, v132
	v_and_b32_e32 v50, 48, v53
	global_load_dwordx4 v[0:3], v[2:3], off
	s_nop 0
	global_load_dwordx4 v[4:7], v[4:5], off
	v_mov_b32_e32 v51, v205
	v_lshl_add_u64 v[10:11], s[4:5], 0, v[10:11]
	v_mad_i64_i32 v[18:19], s[28:29], v18, s70, v[24:25]
	v_lshl_add_u64 v[8:9], v[8:9], 0, v[50:51]
	v_lshl_add_u64 v[12:13], v[10:11], 0, v[48:49]
	v_lshl_add_u64 v[20:21], v[18:19], 0, v[50:51]
	global_load_dwordx4 v[8:11], v[8:9], off offset:128
	s_nop 0
	global_load_dwordx4 v[12:15], v[12:13], off
	s_nop 0
	global_load_dwordx4 v[16:19], v[16:17], off
	s_nop 0
	global_load_dwordx4 v[20:23], v[20:21], off offset:128
	v_ashrrev_i32_e32 v54, 1, v52
	s_movk_i32 s11, 0xffe0
	v_bfe_u32 v133, v52, 5, 1
	v_bfi_b32 v29, s11, v54, v52
	v_mov_b64_e32 v[26:27], s[12:13]
	v_mad_i64_i32 v[26:27], s[12:13], v29, s70, v[26:27]
	v_lshlrev_b32_e32 v204, 4, v133
	v_lshl_add_u64 v[26:27], v[26:27], 0, v[204:205]
	global_load_dwordx4 v[84:87], v[26:27], off
	global_load_dwordx4 v[80:83], v[26:27], off offset:32
	global_load_dwordx4 v[76:79], v[26:27], off offset:64
	global_load_dwordx4 v[72:75], v[26:27], off offset:96
	global_load_dwordx4 v[68:71], v[26:27], off offset:128
	global_load_dwordx4 v[64:67], v[26:27], off offset:160
	v_and_b32_e32 v26, 0xfffff0, v130
	v_lshlrev_b32_e32 v27, 1, v130
	v_and_or_b32 v26, v27, 8, v26
	v_lshrrev_b32_e32 v26, 1, v26
	v_bfe_u32 v28, v28, 5, 1
	v_lshrrev_b32_e32 v27, 1, v130
	v_or_b32_e32 v26, v26, v28
	v_and_b32_e32 v28, 3, v130
	v_and_or_b32 v27, v27, 4, v28
	v_and_b32_e32 v28, 48, v48
	v_lshl_or_b32 v27, v27, 6, v28
	v_lshlrev_b32_e32 v28, 4, v130
	v_lshl_or_b32 v26, v26, 9, v27
	v_lshlrev_b32_e32 v27, 8, v130
	v_and_b32_e32 v28, 0xf0, v28
	s_or_b32 s12, s10, 0x80
	v_bitop3_b32 v27, v48, v27, v28 bitop3:0xde
	v_lshlrev_b32_e32 v30, 2, v52
	v_add_u32_e32 v145, 0, v26
	s_ashr_i32 s13, s12, 31
	v_lshlrev_b32_e32 v28, 8, v132
	v_or_b32_e32 v29, 0x80, v50
	v_and_b32_e32 v30, 0xf0, v30
	s_waitcnt vmcnt(0)
	v_add_u32_e32 v146, 0, v27
	v_bitop3_b32 v28, v29, v28, v30 bitop3:0xde
	v_add_u32_e32 v147, 0, v28
	v_and_b32_e32 v140, 31, v52
	v_and_b32_e32 v56, 63, v52
	v_and_b32_e32 v128, 0xffffffe0, v54
	v_readlane_b32 s76, v255, 19
	v_readlane_b32 s77, v255, 20
	v_readlane_b32 s78, v255, 21
	v_readlane_b32 s79, v255, 22
	v_readlane_b32 s80, v255, 23
	v_readlane_b32 s81, v255, 24
	v_readlane_b32 s82, v255, 25
	v_readlane_b32 s83, v255, 26
	v_readlane_b32 s84, v255, 27
	v_readlane_b32 s85, v255, 28
	v_readlane_b32 s86, v255, 29
	v_readlane_b32 s87, v255, 30
	v_readlane_b32 s88, v255, 31
	v_readlane_b32 s89, v255, 32
	v_readlane_b32 s90, v255, 33
	v_readlane_b32 s91, v255, 34
	s_mov_b32 s76, s77
	s_mov_b32 s78, s77
	s_mov_b32 s79, s77
	s_mov_b32 s80, s77
	s_mov_b32 s81, s77
	s_mov_b32 s82, s77
	s_mov_b32 s83, s77
	s_mov_b32 s84, s77
	s_mov_b32 s85, s77
	s_mov_b32 s86, s77
	s_mov_b32 s87, s77
	s_mov_b32 s88, s77
	s_waitcnt vmcnt(0)
; #define SLOAD(i, j) do { const long kr_ = KROW(j); sr_[i].vs0 = ld8(Vp + (kr_ + sr) * ldv + sc); sr_[i].ks0 = ld8(Kp + (kr_ + sr) * ldk + sc); \
;     if (DQK == 96) sr_[i].ks1 = ld8(Kp + (kr_ + sr2) * ldk + sc2); } while (0)
; #define SWRITE(b, i) do { *(bf16x8*)(V_lds + (b) * SHM_V + vst0) = sr_[i].vs0; *(bf16x8*)(K_lds + (b) * SHM_K + kst0) = sr_[i].ks0; \
;     if (DQK == 96) *(bf16x8*)(K_lds + (b) * SHM_K + kst1) = sr_[i].ks1; } while (0)
; template <int DQK, int MODE, int ldq, int ldk, int ldv> ...
;     ...
;   const bf16_t* Qw = Qb + (long)(wid * QBLK + r32) * ldq + hi * 8;
; #pragma unroll
;   for (int d0 = 0; d0 < DQK / 16; ++d0) qr[d0] = ld8(Qw + d0 * 16);
;     ...
;   f32x16 pA0, pA1, pB0, pB1; float mnA, mnB, alA, alB; bf16x8 pa0, pa1, pa2, pa3;
;   constexpr int SE = 0, SO = 1;
;   SLOAD(SE, 0); SLOAD(SO, 1); asm volatile("s_waitcnt vmcnt(0)" ::: "memory"); SWRITE(0, SE); SWRITE(1, SO);
;   if (2 < NT) SLOAD(SE, 2);
	ds_write_b128 v145, v[0:3]
	v_lshl_add_u64 v[0:1], v[130:131], 0, s[12:13]
	ds_write_b128 v146, v[4:7] offset:32768
	v_lshlrev_b64 v[2:3], 9, v[0:1]
	v_mad_u64_u32 v[4:5], s[28:29], v0, s70, v[24:25]
	v_lshl_add_u64 v[2:3], s[4:5], 0, v[2:3]
	v_mad_i32_i24 v5, v1, s70, v5
	ds_write_b128 v147, v[8:11] offset:32768
	ds_write_b128 v145, v[12:15] offset:16384
	ds_write_b128 v146, v[16:19] offset:49152
	ds_write_b128 v147, v[20:23] offset:49152
	v_lshl_add_u64 v[2:3], v[2:3], 0, v[48:49]
	s_mov_b32 s98, 0xffff8000
	s_mov_b32 s99, -1
	v_lshl_add_u64 v[2:3], v[2:3], 0, s[98:99]
	v_lshl_add_u64 v[0:1], v[4:5], 0, v[48:49]
	global_load_dwordx4 v[92:95], v[2:3], off
	global_load_dwordx4 v[88:91], v[0:1], off
	v_or_b32_e32 v0, s12, v132
	v_mad_i64_i32 v[0:1], s[12:13], v0, s70, v[24:25]
	v_lshl_add_u64 v[0:1], v[0:1], 0, v[50:51]
	v_lshlrev_b32_e32 v8, 8, v140
	v_and_b32_e32 v9, 0xf0, v53
	global_load_dwordx4 v[96:99], v[0:1], off offset:128
	v_bitop3_b32 v0, v204, v8, v9 bitop3:0xde
	v_add_u32_e32 v148, 0, v0
	v_lshlrev_b32_e32 v12, 16, v64
	v_and_b32_e32 v13, 0xffff0000, v64
	v_mul_f32_e32 v12, 0x3e16c740, v12
	v_mul_f32_e32 v13, 0x3e16c740, v13
	v_cvt_pk_bf16_f32 v64, v12, v13
	v_lshlrev_b32_e32 v12, 16, v65
	v_and_b32_e32 v13, 0xffff0000, v65
	v_mul_f32_e32 v12, 0x3e16c740, v12
	v_mul_f32_e32 v13, 0x3e16c740, v13
	v_cvt_pk_bf16_f32 v65, v12, v13
	v_lshlrev_b32_e32 v12, 16, v66
	v_and_b32_e32 v13, 0xffff0000, v66
	v_mul_f32_e32 v12, 0x3e16c740, v12
	v_mul_f32_e32 v13, 0x3e16c740, v13
	v_cvt_pk_bf16_f32 v66, v12, v13
	v_lshlrev_b32_e32 v12, 16, v67
	v_and_b32_e32 v13, 0xffff0000, v67
	v_mul_f32_e32 v12, 0x3e16c740, v12
	v_mul_f32_e32 v13, 0x3e16c740, v13
	v_cvt_pk_bf16_f32 v67, v12, v13
	v_lshlrev_b32_e32 v12, 16, v68
	v_and_b32_e32 v13, 0xffff0000, v68
	v_mul_f32_e32 v12, 0x3e16c740, v12
	v_mul_f32_e32 v13, 0x3e16c740, v13
	v_cvt_pk_bf16_f32 v68, v12, v13
	v_lshlrev_b32_e32 v12, 16, v69
	v_and_b32_e32 v13, 0xffff0000, v69
	v_mul_f32_e32 v12, 0x3e16c740, v12
	v_mul_f32_e32 v13, 0x3e16c740, v13
	v_cvt_pk_bf16_f32 v69, v12, v13
	v_lshlrev_b32_e32 v12, 16, v70
	v_and_b32_e32 v13, 0xffff0000, v70
	v_mul_f32_e32 v12, 0x3e16c740, v12
	v_mul_f32_e32 v13, 0x3e16c740, v13
	v_cvt_pk_bf16_f32 v70, v12, v13
	v_lshlrev_b32_e32 v12, 16, v71
	v_and_b32_e32 v13, 0xffff0000, v71
	v_mul_f32_e32 v12, 0x3e16c740, v12
	v_mul_f32_e32 v13, 0x3e16c740, v13
	v_cvt_pk_bf16_f32 v71, v12, v13
	v_lshlrev_b32_e32 v12, 16, v72
	v_and_b32_e32 v13, 0xffff0000, v72
	v_mul_f32_e32 v12, 0x3e16c740, v12
	v_mul_f32_e32 v13, 0x3e16c740, v13
	v_cvt_pk_bf16_f32 v72, v12, v13
	v_lshlrev_b32_e32 v12, 16, v73
	v_and_b32_e32 v13, 0xffff0000, v73
	v_mul_f32_e32 v12, 0x3e16c740, v12
	v_mul_f32_e32 v13, 0x3e16c740, v13
	v_cvt_pk_bf16_f32 v73, v12, v13
	v_lshlrev_b32_e32 v12, 16, v74
	v_and_b32_e32 v13, 0xffff0000, v74
	v_mul_f32_e32 v12, 0x3e16c740, v12
	v_mul_f32_e32 v13, 0x3e16c740, v13
	v_cvt_pk_bf16_f32 v74, v12, v13
	v_lshlrev_b32_e32 v12, 16, v75
	v_and_b32_e32 v13, 0xffff0000, v75
	v_mul_f32_e32 v12, 0x3e16c740, v12
	v_mul_f32_e32 v13, 0x3e16c740, v13
	v_cvt_pk_bf16_f32 v75, v12, v13
	v_lshlrev_b32_e32 v12, 16, v76
	v_and_b32_e32 v13, 0xffff0000, v76
	v_mul_f32_e32 v12, 0x3e16c740, v12
	v_mul_f32_e32 v13, 0x3e16c740, v13
	v_cvt_pk_bf16_f32 v76, v12, v13
	v_lshlrev_b32_e32 v12, 16, v77
	v_and_b32_e32 v13, 0xffff0000, v77
	v_mul_f32_e32 v12, 0x3e16c740, v12
	v_mul_f32_e32 v13, 0x3e16c740, v13
	v_cvt_pk_bf16_f32 v77, v12, v13
	v_lshlrev_b32_e32 v12, 16, v78
	v_and_b32_e32 v13, 0xffff0000, v78
	v_mul_f32_e32 v12, 0x3e16c740, v12
	v_mul_f32_e32 v13, 0x3e16c740, v13
	v_cvt_pk_bf16_f32 v78, v12, v13
	v_lshlrev_b32_e32 v12, 16, v79
	v_and_b32_e32 v13, 0xffff0000, v79
	v_mul_f32_e32 v12, 0x3e16c740, v12
	v_mul_f32_e32 v13, 0x3e16c740, v13
	v_cvt_pk_bf16_f32 v79, v12, v13
	v_lshlrev_b32_e32 v12, 16, v80
	v_and_b32_e32 v13, 0xffff0000, v80
	v_mul_f32_e32 v12, 0x3e16c740, v12
	v_mul_f32_e32 v13, 0x3e16c740, v13
	v_cvt_pk_bf16_f32 v80, v12, v13
	v_lshlrev_b32_e32 v12, 16, v81
	v_and_b32_e32 v13, 0xffff0000, v81
	v_mul_f32_e32 v12, 0x3e16c740, v12
	v_mul_f32_e32 v13, 0x3e16c740, v13
	v_cvt_pk_bf16_f32 v81, v12, v13
	v_lshlrev_b32_e32 v12, 16, v82
	v_and_b32_e32 v13, 0xffff0000, v82
	v_mul_f32_e32 v12, 0x3e16c740, v12
	v_mul_f32_e32 v13, 0x3e16c740, v13
	v_cvt_pk_bf16_f32 v82, v12, v13
	v_lshlrev_b32_e32 v12, 16, v83
	v_and_b32_e32 v13, 0xffff0000, v83
	v_mul_f32_e32 v12, 0x3e16c740, v12
	v_mul_f32_e32 v13, 0x3e16c740, v13
	v_cvt_pk_bf16_f32 v83, v12, v13
	v_lshlrev_b32_e32 v12, 16, v84
	v_and_b32_e32 v13, 0xffff0000, v84
	v_mul_f32_e32 v12, 0x3e16c740, v12
	v_mul_f32_e32 v13, 0x3e16c740, v13
	v_cvt_pk_bf16_f32 v84, v12, v13
	v_lshlrev_b32_e32 v12, 16, v85
	v_and_b32_e32 v13, 0xffff0000, v85
	v_mul_f32_e32 v12, 0x3e16c740, v12
	v_mul_f32_e32 v13, 0x3e16c740, v13
	v_cvt_pk_bf16_f32 v85, v12, v13
	v_lshlrev_b32_e32 v12, 16, v86
	v_and_b32_e32 v13, 0xffff0000, v86
	v_mul_f32_e32 v12, 0x3e16c740, v12
	v_mul_f32_e32 v13, 0x3e16c740, v13
	v_cvt_pk_bf16_f32 v86, v12, v13
	v_lshlrev_b32_e32 v12, 16, v87
	v_and_b32_e32 v13, 0xffff0000, v87
	v_mul_f32_e32 v12, 0x3e16c740, v12
	v_mul_f32_e32 v13, 0x3e16c740, v13
	v_cvt_pk_bf16_f32 v87, v12, v13
	s_waitcnt lgkmcnt(0)
	s_barrier
; template <int DQK> __device__ __forceinline__ void partialSM(f32x16& p0, f32x16& p1, float& m_reg, float& mn, float& alpha) {
;   constexpr float SCALE = (DQK == 96) ? 0.10206207261596577f : 0.125f;
;   constexpr float C = SCALE * 1.4426950408889634f;
;   float pmax = p0[0];
; #pragma unroll
;   for (int r = 1; r < 16; ++r) pmax = fmaxf(pmax, p0[r]);
; #pragma unroll
;   for (int r = 0; r < 16; ++r) pmax = fmaxf(pmax, p1[r]);
;   { auto rr = __builtin_amdgcn_permlane32_swap(__float_as_uint(pmax), __float_as_uint(pmax), false, false);
;     pmax = fmaxf(__uint_as_float(rr[0]), __uint_as_float(rr[1])); }
;   if (__builtin_expect(__all(pmax - m_reg <= THR / SCALE), 1)) { mn = m_reg; alpha = 1.f; }
;   else { mn = fmaxf(m_reg, pmax); alpha = __builtin_amdgcn_exp2f((m_reg - mn) * C); m_reg = mn; }
;   float mnC = -mn * C;
; #pragma unroll
;   for (int r = 0; r < 16; ++r) p0[r] = fmaf(p0[r], C, mnC);
; #pragma unroll
;   for (int r = 0; r < 16; ++r) p1[r] = fmaf(p1[r], C, mnC);
; #pragma unroll
;   for (int r = 0; r < 16; ++r) p0[r] = __builtin_amdgcn_exp2f(p0[r]);
; template <int DQK> __device__ __forceinline__ void qkt(f32x16& p0, f32x16& p1, const char* Ks, const bf16x8* qr, int r32, int hi) {
;   p0 = f32x16{}; p1 = f32x16{};
; #pragma unroll
;   for (int d0 = 0; d0 < DQK / 16; ++d0) { int cb = (d0 * 16 + hi * 8) * 2;
;     bf16x8 b0 = *reinterpret_cast<const bf16x8*>(Ks + KSWZ(r32, cb));
;     bf16x8 b1 = *reinterpret_cast<const bf16x8*>(Ks + KSWZ(32 + r32, cb));
;     p0 = __builtin_amdgcn_mfma_f32_32x32x16_bf16(b0, qr[d0], p0, 0, 0, 0);
;     p1 = __builtin_amdgcn_mfma_f32_32x32x16_bf16(b1, qr[d0], p1, 0, 0, 0); }
	ds_read_b128 v[0:3], v148 offset:32768
	ds_read_b128 v[4:7], v148 offset:40960
	s_waitcnt lgkmcnt(1)
	v_mfma_f32_32x32x16_bf16 v[32:47], v[0:3], v[84:87], 0
	v_or_b32_e32 v0, 32, v204
	v_bitop3_b32 v0, v0, v8, v9 bitop3:0xde
	v_add_u32_e32 v152, 0, v0
	v_lshlrev_b32_e32 v10, 3, v56
	v_and_b32_e32 v11, 0xc0, v53
	s_mov_b32 s89, s77
	s_mov_b32 s90, s77
	s_waitcnt lgkmcnt(0)
	v_mfma_f32_32x32x16_bf16 v[16:31], v[4:7], v[84:87], 0
	ds_read_b128 v[0:3], v152 offset:32768
	ds_read_b128 v[4:7], v152 offset:40960
	s_mov_b32 s91, s77
	v_lshl_add_u64 v[134:135], s[4:5], 0, v[48:49]
	v_lshl_add_u64 v[136:137], s[0:1], 0, v[48:49]
	s_mov_b32 s13, s77
	s_mov_b32 s11, 4
	v_lshl_add_u64 v[138:139], s[0:1], 0, v[50:51]
	s_sub_u32 s98, s0, s18
	s_sub_u32 s99, s4, s20
	v_mad_u32_u24 v134, v130, s70, v48
	v_lshl_add_u32 v135, v130, 9, v48
	v_mad_u32_u24 v238, v132, s70, v50
	v_add_u32_e32 v134, s98, v134
	v_add_u32_e32 v135, s99, v135
	v_add_u32_e32 v238, s98, v238
	s_waitcnt lgkmcnt(1)
	v_mfma_f32_32x32x16_bf16 v[32:47], v[0:3], v[80:83], v[32:47]
	v_or_b32_e32 v0, 64, v204
	v_bitop3_b32 v0, v0, v8, v9 bitop3:0xde
	v_add_u32_e32 v151, 0, v0
	v_cmp_gt_u32_e64 s[4:5], 32, v56
	v_mov_b32_e32 v142, 0
	s_waitcnt lgkmcnt(0)
	v_mfma_f32_32x32x16_bf16 v[16:31], v[4:7], v[80:83], v[16:31]
	ds_read_b128 v[0:3], v151 offset:32768
	ds_read_b128 v[4:7], v151 offset:40960
	s_waitcnt lgkmcnt(1)
	v_mfma_f32_32x32x16_bf16 v[32:47], v[0:3], v[76:79], v[32:47]
	v_or_b32_e32 v0, 0x60, v204
	v_bitop3_b32 v0, v0, v8, v9 bitop3:0xde
	v_add_u32_e32 v149, 0, v0
	ds_read_b128 v[0:3], v149 offset:32768
	s_waitcnt lgkmcnt(1)
	v_mfma_f32_32x32x16_bf16 v[16:31], v[4:7], v[76:79], v[16:31]
	v_and_b32_e32 v4, 0x3fffffc0, v52
	v_lshl_add_u32 v57, v4, 2, s26
	ds_read_b128 v[4:7], v149 offset:40960
	v_lshl_add_u32 v141, v140, 2, v57
	v_add_u32_e32 v129, v57, v204
	s_waitcnt lgkmcnt(1)
	v_mfma_f32_32x32x16_bf16 v[32:47], v[0:3], v[72:75], v[32:47]
	v_or_b32_e32 v0, 0x80, v204
	v_bitop3_b32 v0, v0, v8, v9 bitop3:0xde
	v_add_u32_e32 v150, 0, v0
	ds_read_b128 v[0:3], v150 offset:32768
	s_waitcnt lgkmcnt(1)
	v_mfma_f32_32x32x16_bf16 v[16:31], v[4:7], v[72:75], v[16:31]
	v_lshlrev_b32_e32 v5, 1, v52
	v_and_or_b32 v4, v10, 24, v11
	v_and_b32_e32 v5, 32, v5
	v_and_b32_e32 v6, 0x100, v10
	v_or3_b32 v58, v4, v5, v6
	ds_read_b128 v[4:7], v150 offset:40960
	v_add_u32_e32 v144, s25, v58
	s_waitcnt lgkmcnt(1)
	v_mfma_f32_32x32x16_bf16 v[32:47], v[0:3], v[68:71], v[32:47]
	v_or_b32_e32 v0, 0xa0, v204
	v_bitop3_b32 v0, v0, v8, v9 bitop3:0xde
	v_add_u32_e32 v153, 0, v0
	ds_read_b128 v[0:3], v153 offset:32768
	ds_read_b128 v[52:55], v153 offset:40960
	v_writelane_b32 v255, s12, 19
	s_waitcnt lgkmcnt(2)
	v_mfma_f32_32x32x16_bf16 v[16:31], v[4:7], v[68:71], v[16:31]
	v_writelane_b32 v255, s13, 20
	v_writelane_b32 v255, s14, 21
	v_writelane_b32 v255, s15, 22
	v_writelane_b32 v255, s16, 23
	v_writelane_b32 v255, s17, 24
	v_writelane_b32 v255, s18, 25
	v_writelane_b32 v255, s19, 26
	s_waitcnt lgkmcnt(1)
	v_mfma_f32_32x32x16_bf16 v[32:47], v[0:3], v[64:67], v[32:47]
	v_mov_b64_e32 v[0:1], s[76:77]
	v_mov_b64_e32 v[2:3], s[78:79]
	v_mov_b64_e32 v[4:5], s[80:81]
	v_mov_b64_e32 v[6:7], s[82:83]
	v_mov_b64_e32 v[8:9], s[84:85]
	v_mov_b64_e32 v[10:11], s[86:87]
	v_mov_b64_e32 v[12:13], s[88:89]
	s_waitcnt lgkmcnt(0)
	v_mfma_f32_32x32x16_bf16 v[16:31], v[52:55], v[64:67], v[16:31]
	s_nop 2
	v_max_f32_e32 v52, v33, v33
	v_max_f32_e32 v53, v32, v32
	v_max_f32_e32 v52, v53, v52
	v_max3_f32 v52, v52, v34, v35
	v_max3_f32 v52, v52, v36, v37
	v_max3_f32 v52, v52, v38, v39
	v_max3_f32 v52, v52, v40, v41
	v_max3_f32 v52, v52, v42, v43
	v_max3_f32 v52, v52, v44, v45
	v_max3_f32 v52, v52, v46, v47
	v_max3_f32 v52, v52, v16, v17
	v_max3_f32 v52, v52, v18, v19
	v_max3_f32 v52, v52, v20, v21
	v_max3_f32 v52, v52, v22, v23
	v_max3_f32 v52, v52, v24, v25
	v_max3_f32 v52, v52, v26, v27
	v_max3_f32 v52, v52, v28, v29
	v_max3_f32 v52, v52, v30, v31
	v_mov_b32_e32 v53, v52
	s_nop 1
	v_permlane32_swap_b32_e32 v52, v53
	v_max_f32_e32 v53, v53, v53
	v_max_f32_e32 v52, v52, v52
	v_max_f32_e32 v52, v52, v53
	v_mov_b64_e32 v[14:15], s[90:91]
	s_mov_b32 s80, 0x4138aa3b
	v_add_f32_e32 v53, 0x7149f2ca, v52
	v_cmp_ge_f32_e32 vcc, s80, v53
	s_cmp_eq_u64 vcc, exec
	v_max_f32_e32 v49, 0xf149f2ca, v52
	s_cselect_b64 vcc, -1, 0
	v_cndmask_b32_e32 v116, v49, v248, vcc
	v_mul_f32_e32 v48, 0xbf800000, v116
	v_fmamk_f32 v32, v32, 0x3f800000, v48
	v_exp_f32_e32 v126, v32
	v_fmamk_f32 v32, v33, 0x3f800000, v48
	v_exp_f32_e32 v160, v32
	v_fmamk_f32 v32, v34, 0x3f800000, v48
	v_exp_f32_e32 v127, v32
	v_fmamk_f32 v32, v35, 0x3f800000, v48
	v_exp_f32_e32 v161, v32
	v_fmamk_f32 v32, v36, 0x3f800000, v48
	v_exp_f32_e32 v158, v32
	v_fmamk_f32 v32, v37, 0x3f800000, v48
	v_exp_f32_e32 v162, v32
	v_fmamk_f32 v32, v38, 0x3f800000, v48
	v_exp_f32_e32 v159, v32
	v_fmamk_f32 v32, v39, 0x3f800000, v48
	v_writelane_b32 v255, s20, 27
	v_exp_f32_e32 v163, v32
	v_fmamk_f32 v32, v40, 0x3f800000, v48
	v_writelane_b32 v255, s21, 28
	v_exp_f32_e32 v118, v32
	v_fmamk_f32 v32, v41, 0x3f800000, v48
	v_writelane_b32 v255, s22, 29
	v_exp_f32_e32 v121, v32
	v_fmamk_f32 v32, v42, 0x3f800000, v48
	v_sub_f32_e32 v33, 0xf149f2ca, v49
	v_writelane_b32 v255, s23, 30
	v_exp_f32_e32 v119, v32
	v_fmamk_f32 v32, v43, 0x3f800000, v48
	v_mul_f32_e32 v33, 0x3f800000, v33
	v_writelane_b32 v255, s24, 31
	v_exp_f32_e32 v122, v32
	v_fmamk_f32 v32, v44, 0x3f800000, v48
	v_exp_f32_e32 v33, v33
	v_writelane_b32 v255, s25, 32
	v_exp_f32_e32 v120, v32
	v_fmamk_f32 v32, v45, 0x3f800000, v48
	v_writelane_b32 v255, s26, 33
	v_exp_f32_e32 v123, v32
	v_fmamk_f32 v32, v46, 0x3f800000, v48
	v_writelane_b32 v255, s27, 34
; #define SBAR() __builtin_amdgcn_sched_barrier(0)
; template <int DQK> __device__ __forceinline__ void partialSM(f32x16& p0, f32x16& p1, float& m_reg, float& mn, float& alpha) {
;     ...
;   if (__builtin_expect(__all(pmax - m_reg <= THR / SCALE), 1)) { mn = m_reg; alpha = 1.f; }
;   else { mn = fmaxf(m_reg, pmax); alpha = __builtin_amdgcn_exp2f((m_reg - mn) * C); m_reg = mn; }
;   float mnC = -mn * C;
; #pragma unroll
;   for (int r = 0; r < 16; ++r) p0[r] = fmaf(p0[r], C, mnC);
; #pragma unroll
;   for (int r = 0; r < 16; ++r) p1[r] = fmaf(p1[r], C, mnC);
; #pragma unroll
;   for (int r = 0; r < 16; ++r) p0[r] = __builtin_amdgcn_exp2f(p0[r]);
; template <int DQK, int MODE, int ldq, int ldk, int ldv> ...
;     ...
;   for (int j = 1; j + 1 < NT; j += 2) {
;     SBAR(); qkt<DQK>(pB0, pB1, K_lds + SHM_K, qr, r32, hi);
	v_exp_f32_e32 v124, v32
	v_fmamk_f32 v32, v47, 0x3f800000, v48
	v_fmamk_f32 v100, v30, 0x3f800000, v48
	v_fmamk_f32 v101, v31, 0x3f800000, v48
	v_fmamk_f32 v106, v28, 0x3f800000, v48
	v_fmamk_f32 v107, v29, 0x3f800000, v48
	v_fmamk_f32 v110, v26, 0x3f800000, v48
	v_fmamk_f32 v111, v27, 0x3f800000, v48
	v_fmamk_f32 v102, v24, 0x3f800000, v48
	v_fmamk_f32 v103, v25, 0x3f800000, v48
	v_fmamk_f32 v104, v22, 0x3f800000, v48
	v_fmamk_f32 v105, v23, 0x3f800000, v48
	v_fmamk_f32 v108, v20, 0x3f800000, v48
	v_fmamk_f32 v109, v21, 0x3f800000, v48
	v_fmamk_f32 v112, v18, 0x3f800000, v48
	v_fmamk_f32 v113, v19, 0x3f800000, v48
	v_fmamk_f32 v114, v16, 0x3f800000, v48
	v_fmamk_f32 v115, v17, 0x3f800000, v48
	s_addk_i32 s25, 0x4000
	v_mov_b64_e32 v[30:31], v[14:15]
	s_mov_b64 s[84:85], 0x90000
	s_movk_i32 s83, 0x6000
	s_movk_i32 s82, 0x100
	v_readlane_b32 s89, v255, 47
	v_readlane_b32 s76, v255, 37
	s_movk_i32 s90, 0x1fff
	s_mov_b32 s88, 0x42800000
	s_movk_i32 s87, 0x7000
	s_movk_i32 s86, 0x1200
	s_movk_i32 s81, 0x5000
	s_movk_i32 s78, 0x4000
	v_exp_f32_e32 v125, v32
	v_cndmask_b32_e64 v154, v33, 1.0, vcc
	v_add_u32_e32 v143, s25, v58
	v_mov_b64_e32 v[28:29], v[12:13]
	v_mov_b64_e32 v[26:27], v[10:11]
	v_mov_b64_e32 v[24:25], v[8:9]
	v_mov_b64_e32 v[22:23], v[6:7]
	v_mov_b64_e32 v[20:21], v[4:5]
	v_mov_b64_e32 v[18:19], v[2:3]
	v_mov_b64_e32 v[16:17], v[0:1]
	v_exp_f32_e32 v114, v114
	v_exp_f32_e32 v115, v115
	v_exp_f32_e32 v112, v112
	v_exp_f32_e32 v113, v113
	v_exp_f32_e32 v108, v108
	v_exp_f32_e32 v109, v109
	v_exp_f32_e32 v104, v104
	v_exp_f32_e32 v105, v105
	v_exp_f32_e32 v102, v102
	v_exp_f32_e32 v103, v103
	v_exp_f32_e32 v110, v110
	v_exp_f32_e32 v111, v111
	v_exp_f32_e32 v106, v106
	v_exp_f32_e32 v107, v107
	v_exp_f32_e32 v101, v101
	v_exp_f32_e32 v100, v100
	v_sub_f32_e32 v210, 0, v116
	v_mov_b32_e32 v211, v210
	v_mov_b32_e32 v212, v210
	v_mov_b32_e32 v213, v210
	v_mov_b32_e32 v214, v210
	v_mov_b32_e32 v215, v210
	v_mov_b32_e32 v216, v210
	v_mov_b32_e32 v217, v210
	v_mov_b32_e32 v218, v210
	v_mov_b32_e32 v219, v210
	v_mov_b32_e32 v220, v210
	v_mov_b32_e32 v221, v210
	v_mov_b32_e32 v222, v210
	v_mov_b32_e32 v223, v210
	v_mov_b32_e32 v224, v210
	v_mov_b32_e32 v225, v210
	s_barrier
	.p2align 8
.LBB0_300:
	s_add_i32 s25, s11, -3
	s_cmp_lg_u32 s32, 0
	s_cbranch_scc1 .Lmy_h1B
	ds_read_b128 v[32:35], v148 offset:49152
	ds_read_b128 v[36:39], v148 offset:57344
	ds_read_b128 v[164:167], v152 offset:49152
	ds_read_b128 v[168:171], v152 offset:57344
	s_waitcnt lgkmcnt(3)
	v_mfma_f32_32x32x16_bf16 v[48:63], v[32:35], v[84:87], v[210:225]
	s_waitcnt lgkmcnt(2)
	v_mfma_f32_32x32x16_bf16 v[32:47], v[36:39], v[84:87], v[210:225]
	s_waitcnt lgkmcnt(1)
	v_mfma_f32_32x32x16_bf16 v[48:63], v[164:167], v[80:83], v[48:63]
	s_waitcnt lgkmcnt(0)
	v_mfma_f32_32x32x16_bf16 v[32:47], v[168:171], v[80:83], v[32:47]
	ds_read_b128 v[164:167], v151 offset:49152
	ds_read_b128 v[168:171], v151 offset:57344
	s_waitcnt lgkmcnt(1)
	v_mfma_f32_32x32x16_bf16 v[48:63], v[164:167], v[76:79], v[48:63]
	s_waitcnt lgkmcnt(0)
	v_mfma_f32_32x32x16_bf16 v[32:47], v[168:171], v[76:79], v[32:47]
	ds_read_b128 v[164:167], v149 offset:49152
	ds_read_b128 v[168:171], v149 offset:57344
	s_waitcnt lgkmcnt(1)
	v_mfma_f32_32x32x16_bf16 v[48:63], v[164:167], v[72:75], v[48:63]
	s_waitcnt lgkmcnt(0)
	v_mfma_f32_32x32x16_bf16 v[32:47], v[168:171], v[72:75], v[32:47]
	ds_read_b128 v[164:167], v150 offset:49152
	ds_read_b128 v[168:171], v150 offset:57344
	s_waitcnt lgkmcnt(1)
	v_mfma_f32_32x32x16_bf16 v[48:63], v[164:167], v[68:71], v[48:63]
	s_waitcnt lgkmcnt(0)
	v_mfma_f32_32x32x16_bf16 v[32:47], v[168:171], v[68:71], v[32:47]
	ds_read_b128 v[164:167], v153 offset:49152
	ds_read_b128 v[168:171], v153 offset:57344
	s_waitcnt vmcnt(0)
	ds_write_b128 v146, v[88:91] offset:32768
	ds_write_b128 v147, v[96:99] offset:32768
	ds_write_b128 v145, v[92:95] offset:16384
	s_waitcnt lgkmcnt(4)
	v_mfma_f32_32x32x16_bf16 v[48:63], v[164:167], v[64:67], v[48:63]
	s_waitcnt lgkmcnt(3)
	v_mfma_f32_32x32x16_bf16 v[32:47], v[168:171], v[64:67], v[32:47]
	ds_read_b64_tr_b16 v[184:185], v144 offset:0
	ds_read_b64_tr_b16 v[186:187], v144 offset:0x800
	ds_read_b64_tr_b16 v[188:189], v144 offset:0x1000
	ds_read_b64_tr_b16 v[190:191], v144 offset:0x1800
	ds_read_b64_tr_b16 v[192:193], v144 offset:0x2000
	ds_read_b64_tr_b16 v[194:195], v144 offset:0x2800
	ds_read_b64_tr_b16 v[196:197], v144 offset:0x3000
	ds_read_b64_tr_b16 v[198:199], v144 offset:0x3800
	v_mov_b32_e32 v117, v114
	v_mov_b32_e32 v157, v115
	v_mov_b32_e32 v164, v112
	v_add_f32_e32 v112, 0, v126
	v_add_f32_e32 v112, v160, v112
	v_add_f32_e32 v112, v127, v112
	v_add_f32_e32 v112, v161, v112
	v_add_f32_e32 v112, v158, v112
	v_add_f32_e32 v112, v162, v112
	v_add_f32_e32 v112, v159, v112
	v_add_f32_e32 v112, v163, v112
	v_add_f32_e32 v112, v118, v112
	v_add_f32_e32 v112, v121, v112
	v_add_f32_e32 v112, v119, v112
	v_add_f32_e32 v112, v122, v112
	v_add_f32_e32 v112, v120, v112
	v_add_f32_e32 v112, v123, v112
	v_add_f32_e32 v112, v124, v112
	v_mov_b32_e32 v165, v113
	v_add_f32_e32 v112, v125, v112
	v_add_f32_e32 v112, v117, v112
	v_add_f32_e32 v112, v157, v112
	v_add_f32_e32 v112, v164, v112
	v_add_f32_e32 v112, v165, v112
	v_add_f32_e32 v112, v108, v112
	v_add_f32_e32 v112, v109, v112
	v_add_f32_e32 v112, v104, v112
	v_add_f32_e32 v112, v105, v112
	v_add_f32_e32 v112, v102, v112
	v_add_f32_e32 v112, v103, v112
	v_add_f32_e32 v112, v110, v112
	v_add_f32_e32 v112, v111, v112
	v_add_f32_e32 v112, v106, v112
	v_add_f32_e32 v112, v107, v112
	v_add_f32_e32 v112, v100, v112
	v_add_f32_e32 v155, v101, v112
	v_mov_b32_e32 v156, v155
	v_cvt_pk_bf16_f32 v200, v126, v160
; #define SBAR() __builtin_amdgcn_sched_barrier(0)
; #define SLOAD(i, j) do { const long kr_ = KROW(j); sr_[i].vs0 = ld8(Vp + (kr_ + sr) * ldv + sc); sr_[i].ks0 = ld8(Kp + (kr_ + sr) * ldk + sc); \
;     if (DQK == 96) sr_[i].ks1 = ld8(Kp + (kr_ + sr2) * ldk + sc2); } while (0)
; #define SWRITE(b, i) do { *(bf16x8*)(V_lds + (b) * SHM_V + vst0) = sr_[i].vs0; *(bf16x8*)(K_lds + (b) * SHM_K + kst0) = sr_[i].ks0; \
;     if (DQK == 96) *(bf16x8*)(K_lds + (b) * SHM_K + kst1) = sr_[i].ks1; } while (0)
; #define RESC(a) do { if (__any((a) < 1.f)) { if (hi == 0) al_l[r32] = (a); asm volatile("s_waitcnt lgkmcnt(0)" ::: "memory"); \
;     _Pragma("unroll") for (int d = 0; d < 2; ++d) _Pragma("unroll") for (int r = 0; r < 16; ++r) o[d][r] *= al_l[crow(r, hi)]; } } while (0)
; #define BIAS(P0, P1, j) do { if (MODE == 1) { SBAR(); if ((j) >= nA) na_bias(P0, P1, na, rs0 + (j) - nA, hi); SBAR(); } } while (0)
; template <int DQK, int MODE, int ldq, int ldk, int ldv> ...
;     ...
;   for (int j = 1; j + 1 < NT; j += 2) {
;     SBAR(); qkt<DQK>(pB0, pB1, K_lds + SHM_K, qr, r32, hi);
;     finishSM(pA0, pA1, alA, l_reg, pa0, pa1, pa2, pa3); SBAR();
;     SLOAD(SO, j + 2); SBAR();
;     pv_d0(o, vb0, pa0, pa1, pa2, pa3); BIAS(pB0, pB1, j); partialSM<DQK>(pB0, pB1, m_reg, mnB, alB);
;     __syncthreads(); SWRITE(0, SE);
;     RESC(alB); __syncthreads();
	v_cvt_pk_bf16_f32 v201, v127, v161
	v_cvt_pk_bf16_f32 v202, v158, v162
	s_nop 1
	v_permlane32_swap_b32_e32 v155, v156
	v_cvt_pk_bf16_f32 v203, v159, v163
	v_permlane32_swap_b32_e32 v200, v202
	v_cvt_pk_bf16_f32 v226, v118, v121
	v_cvt_pk_bf16_f32 v227, v119, v122
	v_cvt_pk_bf16_f32 v228, v120, v123
	v_cvt_pk_bf16_f32 v229, v124, v125
	v_cvt_pk_bf16_f32 v230, v117, v157
	v_cvt_pk_bf16_f32 v231, v164, v165
	v_cvt_pk_bf16_f32 v232, v108, v109
	v_cvt_pk_bf16_f32 v233, v104, v105
	v_cvt_pk_bf16_f32 v136, v102, v103
	v_cvt_pk_bf16_f32 v137, v110, v111
	v_cvt_pk_bf16_f32 v138, v106, v107
	v_cvt_pk_bf16_f32 v139, v100, v101
	v_permlane32_swap_b32_e32 v201, v203
	v_permlane32_swap_b32_e32 v226, v228
	v_permlane32_swap_b32_e32 v227, v229
	v_permlane32_swap_b32_e32 v230, v232
	v_permlane32_swap_b32_e32 v231, v233
	v_permlane32_swap_b32_e32 v136, v138
	v_permlane32_swap_b32_e32 v137, v139
	s_cmpk_lt_u32 s25, 0x7e
	s_cselect_b32 s0, 0, 0xffffff80
	s_cselect_b32 s1, s10, s24
	s_add_i32 s0, s0, s11
	s_lshl_b32 s0, s0, 6
	s_add_i32 s0, s0, s1
	s_sub_i32 s0, s0, 64
	s_ashr_i32 s1, s0, 31
	s_cmpk_lt_u32 s25, 0x7f
	s_cselect_b32 s98, 0, 0xffffff80
	s_cselect_b32 s99, s10, s24
	s_add_i32 s98, s98, s11
	s_lshl_b32 s98, s98, 6
	s_add_i32 s98, s98, s99
	s_addk_i32 s98, 0xff80
	s_ashr_i32 s99, s98, 31
	s_mul_i32 s1, s0, 0x300
	s_add_u32 s12, s18, s1
	s_addc_u32 s13, s19, 0
	s_lshl_b32 s98, s98, 9
	s_add_u32 s98, s20, s98
	s_addc_u32 s99, s21, 0
	global_load_dwordx4 v[100:103], v134, s[12:13]
	global_load_dwordx4 v[108:111], v135, s[98:99]
	global_load_dwordx4 v[104:107], v238, s[12:13] offset:128
	s_waitcnt lgkmcnt(0)
	s_nop 0
	v_mfma_f32_32x32x16_bf16 v[0:15], v[200:203], v[184:187], v[0:15]
	ds_read_b64_tr_b16 v[184:185], v144 offset:0x200
	ds_read_b64_tr_b16 v[186:187], v144 offset:0xa00
	v_max_f32_e32 v112, v48, v49
	v_max3_f32 v112, v112, v50, v51
	v_max3_f32 v112, v112, v52, v53
	v_max3_f32 v112, v112, v54, v55
	v_max3_f32 v112, v112, v56, v57
	v_mfma_f32_32x32x16_bf16 v[0:15], v[226:229], v[188:191], v[0:15]
	ds_read_b64_tr_b16 v[188:189], v144 offset:0x1200
	ds_read_b64_tr_b16 v[190:191], v144 offset:0x1a00
	v_max3_f32 v112, v112, v58, v59
	v_max3_f32 v112, v112, v60, v61
	v_max3_f32 v112, v112, v62, v63
	v_max3_f32 v112, v112, v32, v33
	v_max3_f32 v112, v112, v34, v35
	v_mfma_f32_32x32x16_bf16 v[0:15], v[230:233], v[192:195], v[0:15]
	ds_read_b64_tr_b16 v[192:193], v144 offset:0x2200
	ds_read_b64_tr_b16 v[194:195], v144 offset:0x2a00
	v_max3_f32 v112, v112, v36, v37
	v_max3_f32 v112, v112, v38, v39
	v_max3_f32 v112, v112, v40, v41
	v_max3_f32 v112, v112, v42, v43
	v_max3_f32 v112, v112, v44, v45
	v_mfma_f32_32x32x16_bf16 v[0:15], v[136:139], v[196:199], v[0:15]
	ds_read_b64_tr_b16 v[196:197], v144 offset:0x3200
	ds_read_b64_tr_b16 v[198:199], v144 offset:0x3a00
	v_max3_f32 v112, v112, v46, v47
	v_mov_b32_e32 v113, v112
	s_nop 1
	v_permlane32_swap_b32_e32 v112, v113
	v_max_f32_e32 v112, v112, v113
	v_cmp_ge_f32_e32 vcc, s80, v112
	s_cmp_eq_u64 vcc, exec
	s_cbranch_scc0 .Lmy_rare_a1
	v_mov_b32_e32 v157, 1.0
.Lmy_join_a1:
	v_cmp_gt_f32_e32 vcc, 1.0, v157
	s_waitcnt lgkmcnt(0)
	v_mfma_f32_32x32x16_bf16 v[16:31], v[200:203], v[184:187], v[16:31]
	v_exp_f32_e32 v112, v48
	v_exp_f32_e32 v127, v49
	v_exp_f32_e32 v113, v50
	v_exp_f32_e32 v126, v51
	v_exp_f32_e32 v114, v52
	v_exp_f32_e32 v125, v53
	v_exp_f32_e32 v115, v54
	v_exp_f32_e32 v124, v55
	v_mfma_f32_32x32x16_bf16 v[16:31], v[226:229], v[188:191], v[16:31]
	v_exp_f32_e32 v116, v56
	v_exp_f32_e32 v123, v57
	v_exp_f32_e32 v117, v58
	v_exp_f32_e32 v122, v59
	v_exp_f32_e32 v118, v60
	v_exp_f32_e32 v121, v61
	v_exp_f32_e32 v119, v62
	v_exp_f32_e32 v120, v63
	v_mfma_f32_32x32x16_bf16 v[16:31], v[230:233], v[192:195], v[16:31]
	v_exp_f32_e32 v164, v42
	v_exp_f32_e32 v165, v43
	v_exp_f32_e32 v167, v32
	v_exp_f32_e32 v168, v33
	v_exp_f32_e32 v169, v34
	v_exp_f32_e32 v170, v35
	v_exp_f32_e32 v171, v36
	v_exp_f32_e32 v172, v37
	v_mfma_f32_32x32x16_bf16 v[16:31], v[136:139], v[196:199], v[16:31]
	v_exp_f32_e32 v160, v38
	v_exp_f32_e32 v161, v39
	v_exp_f32_e32 v162, v40
	v_exp_f32_e32 v163, v41
	v_exp_f32_e32 v166, v44
	v_exp_f32_e32 v173, v45
	v_exp_f32_e32 v174, v46
	v_exp_f32_e32 v159, v47
	s_cbranch_vccz .LBB0_304
	s_and_saveexec_b64 s[12:13], s[4:5]
	ds_write_b32 v141, v157 offset:128
	s_or_b64 exec, exec, s[12:13]
	s_waitcnt lgkmcnt(0)
	ds_read_b128 v[184:187], v129 offset:224
	ds_read_b128 v[188:191], v129 offset:192
	ds_read_b128 v[192:195], v129 offset:160
	ds_read_b128 v[196:199], v129 offset:128
	s_waitcnt lgkmcnt(3)
	v_pk_mul_f32 v[14:15], v[14:15], v[186:187]
	s_waitcnt lgkmcnt(2)
	v_pk_mul_f32 v[10:11], v[10:11], v[190:191]
	s_waitcnt lgkmcnt(1)
	v_pk_mul_f32 v[6:7], v[6:7], v[194:195]
	s_waitcnt lgkmcnt(0)
	v_pk_mul_f32 v[2:3], v[2:3], v[198:199]
	v_pk_mul_f32 v[12:13], v[12:13], v[184:185]
	v_pk_mul_f32 v[8:9], v[8:9], v[188:189]
	v_pk_mul_f32 v[4:5], v[4:5], v[192:193]
	v_pk_mul_f32 v[0:1], v[0:1], v[196:197]
	v_pk_mul_f32 v[30:31], v[30:31], v[186:187]
	v_pk_mul_f32 v[26:27], v[26:27], v[190:191]
	v_pk_mul_f32 v[22:23], v[22:23], v[194:195]
	v_pk_mul_f32 v[18:19], v[18:19], v[198:199]
	v_pk_mul_f32 v[28:29], v[28:29], v[184:185]
	v_pk_mul_f32 v[24:25], v[24:25], v[188:189]
	v_pk_mul_f32 v[20:21], v[20:21], v[192:193]
	v_pk_mul_f32 v[16:17], v[16:17], v[196:197]
; #define SBAR() __builtin_amdgcn_sched_barrier(0)
; #define SLOAD(i, j) do { const long kr_ = KROW(j); sr_[i].vs0 = ld8(Vp + (kr_ + sr) * ldv + sc); sr_[i].ks0 = ld8(Kp + (kr_ + sr) * ldk + sc); \
;     if (DQK == 96) sr_[i].ks1 = ld8(Kp + (kr_ + sr2) * ldk + sc2); } while (0)
; #define SWRITE(b, i) do { *(bf16x8*)(V_lds + (b) * SHM_V + vst0) = sr_[i].vs0; *(bf16x8*)(K_lds + (b) * SHM_K + kst0) = sr_[i].ks0; \
;     if (DQK == 96) *(bf16x8*)(K_lds + (b) * SHM_K + kst1) = sr_[i].ks1; } while (0)
; #define RESC(a) do { if (__any((a) < 1.f)) { if (hi == 0) al_l[r32] = (a); asm volatile("s_waitcnt lgkmcnt(0)" ::: "memory"); \
;     _Pragma("unroll") for (int d = 0; d < 2; ++d) _Pragma("unroll") for (int r = 0; r < 16; ++r) o[d][r] *= al_l[crow(r, hi)]; } } while (0)
; template <int DQK, int MODE, int ldq, int ldk, int ldv> ...
;     ...
;     __syncthreads(); SWRITE(0, SE);
;     RESC(alB); __syncthreads();
;     SBAR(); qkt<DQK>(pA0, pA1, K_lds, qr, r32, hi);
;     finishSM(pB0, pB1, alB, l_reg, pa0, pa1, pa2, pa3); SBAR();
;     if (j + 3 < NT) SLOAD(SE, j + 3); SBAR();
.LBB0_304:
	s_waitcnt lgkmcnt(0)
	s_barrier
	ds_read_b128 v[32:35], v148 offset:32768
	ds_read_b128 v[36:39], v148 offset:40960
	ds_read_b128 v[176:179], v152 offset:32768
	ds_read_b128 v[180:183], v152 offset:40960
	s_waitcnt lgkmcnt(3)
	v_mfma_f32_32x32x16_bf16 v[48:63], v[32:35], v[84:87], v[210:225]
	s_waitcnt lgkmcnt(2)
	v_mfma_f32_32x32x16_bf16 v[32:47], v[36:39], v[84:87], v[210:225]
	s_waitcnt lgkmcnt(1)
	v_mfma_f32_32x32x16_bf16 v[48:63], v[176:179], v[80:83], v[48:63]
	s_waitcnt lgkmcnt(0)
	v_mfma_f32_32x32x16_bf16 v[32:47], v[180:183], v[80:83], v[32:47]
	ds_read_b128 v[176:179], v151 offset:32768
	ds_read_b128 v[180:183], v151 offset:40960
	s_waitcnt lgkmcnt(1)
	v_mfma_f32_32x32x16_bf16 v[48:63], v[176:179], v[76:79], v[48:63]
	s_waitcnt lgkmcnt(0)
	v_mfma_f32_32x32x16_bf16 v[32:47], v[180:183], v[76:79], v[32:47]
	ds_read_b128 v[176:179], v149 offset:32768
	ds_read_b128 v[180:183], v149 offset:40960
	s_waitcnt lgkmcnt(1)
	v_mfma_f32_32x32x16_bf16 v[48:63], v[176:179], v[72:75], v[48:63]
	s_waitcnt lgkmcnt(0)
	v_mfma_f32_32x32x16_bf16 v[32:47], v[180:183], v[72:75], v[32:47]
	ds_read_b128 v[176:179], v150 offset:32768
	ds_read_b128 v[180:183], v150 offset:40960
	s_waitcnt lgkmcnt(1)
	v_mfma_f32_32x32x16_bf16 v[48:63], v[176:179], v[68:71], v[48:63]
	s_waitcnt lgkmcnt(0)
	v_mfma_f32_32x32x16_bf16 v[32:47], v[180:183], v[68:71], v[32:47]
	ds_read_b128 v[176:179], v153 offset:32768
	ds_read_b128 v[180:183], v153 offset:40960
	s_waitcnt vmcnt(0)
	ds_write_b128 v146, v[100:103] offset:49152
	ds_write_b128 v147, v[104:107] offset:49152
	ds_write_b128 v145, v[108:111]
	s_waitcnt lgkmcnt(4)
	v_mfma_f32_32x32x16_bf16 v[48:63], v[176:179], v[64:67], v[48:63]
	s_waitcnt lgkmcnt(3)
	v_mfma_f32_32x32x16_bf16 v[32:47], v[180:183], v[64:67], v[32:47]
	ds_read_b64_tr_b16 v[184:185], v143 offset:0
	ds_read_b64_tr_b16 v[186:187], v143 offset:0x800
	ds_read_b64_tr_b16 v[188:189], v143 offset:0x1000
	ds_read_b64_tr_b16 v[190:191], v143 offset:0x1800
	ds_read_b64_tr_b16 v[192:193], v143 offset:0x2000
	ds_read_b64_tr_b16 v[194:195], v143 offset:0x2800
	ds_read_b64_tr_b16 v[196:197], v143 offset:0x3000
	ds_read_b64_tr_b16 v[198:199], v143 offset:0x3800
	v_mov_b32_e32 v175, v164
	v_add_f32_e32 v164, 0, v112
	v_add_f32_e32 v164, v127, v164
	v_add_f32_e32 v164, v113, v164
	v_add_f32_e32 v164, v126, v164
	v_add_f32_e32 v164, v114, v164
	v_add_f32_e32 v164, v125, v164
	v_add_f32_e32 v164, v115, v164
	v_add_f32_e32 v164, v124, v164
	v_add_f32_e32 v164, v116, v164
	v_add_f32_e32 v164, v123, v164
	v_add_f32_e32 v164, v117, v164
	v_add_f32_e32 v164, v122, v164
	v_add_f32_e32 v164, v118, v164
	v_add_f32_e32 v164, v121, v164
	v_add_f32_e32 v164, v119, v164
	v_add_f32_e32 v164, v120, v164
	v_add_f32_e32 v164, v167, v164
	v_add_f32_e32 v164, v168, v164
	v_add_f32_e32 v164, v169, v164
	v_add_f32_e32 v164, v170, v164
	v_add_f32_e32 v164, v171, v164
	v_add_f32_e32 v164, v172, v164
	v_add_f32_e32 v164, v160, v164
	v_add_f32_e32 v164, v161, v164
	v_add_f32_e32 v164, v162, v164
	v_add_f32_e32 v164, v163, v164
	v_add_f32_e32 v164, v175, v164
	v_cvt_pk_bf16_f32 v200, v112, v127
	v_cvt_pk_bf16_f32 v201, v113, v126
	v_cvt_pk_bf16_f32 v202, v114, v125
	v_cvt_pk_bf16_f32 v203, v115, v124
	v_cvt_pk_bf16_f32 v226, v116, v123
	v_cvt_pk_bf16_f32 v227, v117, v122
	v_mov_b32_e32 v176, v165
	v_cvt_pk_bf16_f32 v228, v118, v121
	v_cvt_pk_bf16_f32 v229, v119, v120
	v_cvt_pk_bf16_f32 v230, v167, v168
	v_cvt_pk_bf16_f32 v231, v169, v170
	v_cvt_pk_bf16_f32 v232, v171, v172
	s_nop 0
	v_add_f32_e32 v164, v176, v164
	v_add_f32_e32 v164, v166, v164
	v_add_f32_e32 v164, v173, v164
	v_add_f32_e32 v164, v174, v164
	v_add_f32_e32 v164, v159, v164
	v_mov_b32_e32 v165, v164
	v_cvt_pk_bf16_f32 v233, v160, v161
	v_cvt_pk_bf16_f32 v136, v162, v163
	v_cvt_pk_bf16_f32 v137, v175, v176
	v_cvt_pk_bf16_f32 v138, v166, v173
	v_cvt_pk_bf16_f32 v139, v174, v159
	s_nop 1
	v_permlane32_swap_b32_e32 v164, v165
	v_permlane32_swap_b32_e32 v200, v202
	v_permlane32_swap_b32_e32 v201, v203
	v_permlane32_swap_b32_e32 v226, v228
	v_permlane32_swap_b32_e32 v227, v229
	v_permlane32_swap_b32_e32 v230, v232
	v_permlane32_swap_b32_e32 v231, v233
	v_permlane32_swap_b32_e32 v136, v138
	v_permlane32_swap_b32_e32 v137, v139
	s_cmpk_lt_u32 s25, 0x7e
	s_cselect_b32 s98, 0, 0xffffff80
	s_cselect_b32 s99, s10, s24
	s_add_i32 s98, s98, s11
	s_lshl_b32 s98, s98, 6
	s_add_i32 s98, s98, s99
	s_sub_i32 s98, s98, 64
	s_ashr_i32 s99, s98, 31
	s_lshl_b32 s98, s98, 9
	s_add_u32 s98, s20, s98
	s_addc_u32 s99, s21, 0
	global_load_dwordx4 v[92:95], v135, s[98:99]
	s_cmpk_gt_u32 s25, 0x80
	s_cbranch_scc1 .LBB0_306
	s_cmpk_lt_u32 s25, 0x7d
	s_cselect_b32 s0, 0, 0xffffff80
	s_cselect_b32 s1, s10, s24
	s_add_i32 s0, s0, s11
	s_lshl_b32 s0, s0, 6
	s_add_i32 s0, s0, s1
	s_ashr_i32 s1, s0, 31
	s_mul_i32 s1, s0, 0x300
	s_add_u32 s12, s18, s1
	s_addc_u32 s13, s19, 0
	global_load_dwordx4 v[88:91], v134, s[12:13]
	global_load_dwordx4 v[96:99], v238, s[12:13] offset:128
; #define SWRITE(b, i) do { *(bf16x8*)(V_lds + (b) * SHM_V + vst0) = sr_[i].vs0; *(bf16x8*)(K_lds + (b) * SHM_K + kst0) = sr_[i].ks0; \
;     if (DQK == 96) *(bf16x8*)(K_lds + (b) * SHM_K + kst1) = sr_[i].ks1; } while (0)
; #define RESC(a) do { if (__any((a) < 1.f)) { if (hi == 0) al_l[r32] = (a); asm volatile("s_waitcnt lgkmcnt(0)" ::: "memory"); \
;     _Pragma("unroll") for (int d = 0; d < 2; ++d) _Pragma("unroll") for (int r = 0; r < 16; ++r) o[d][r] *= al_l[crow(r, hi)]; } } while (0)
; #define BIAS(P0, P1, j) do { if (MODE == 1) { SBAR(); if ((j) >= nA) na_bias(P0, P1, na, rs0 + (j) - nA, hi); SBAR(); } } while (0)
; template <int DQK, int MODE, int ldq, int ldk, int ldv> ...
;     ...
;     pv_d0(o, vb0 + (int)SHM_V, pa0, pa1, pa2, pa3); BIAS(pA0, pA1, j + 1); partialSM<DQK>(pA0, pA1, m_reg, mnA, alA);
;     __syncthreads(); SWRITE(1, SO);
;     RESC(alA); __syncthreads();
.LBB0_306:
	s_waitcnt lgkmcnt(0)
	s_nop 0
	v_mfma_f32_32x32x16_bf16 v[0:15], v[200:203], v[184:187], v[0:15]
	ds_read_b64_tr_b16 v[184:185], v143 offset:0x200
	ds_read_b64_tr_b16 v[186:187], v143 offset:0xa00
	v_max_f32_e32 v112, v48, v49
	v_max3_f32 v112, v112, v50, v51
	v_max3_f32 v112, v112, v52, v53
	v_max3_f32 v112, v112, v54, v55
	v_max3_f32 v112, v112, v56, v57
	v_mfma_f32_32x32x16_bf16 v[0:15], v[226:229], v[188:191], v[0:15]
	ds_read_b64_tr_b16 v[188:189], v143 offset:0x1200
	ds_read_b64_tr_b16 v[190:191], v143 offset:0x1a00
	v_max3_f32 v112, v112, v58, v59
	v_max3_f32 v112, v112, v60, v61
	v_max3_f32 v112, v112, v62, v63
	v_max3_f32 v112, v112, v32, v33
	v_max3_f32 v112, v112, v34, v35
	v_mfma_f32_32x32x16_bf16 v[0:15], v[230:233], v[192:195], v[0:15]
	ds_read_b64_tr_b16 v[192:193], v143 offset:0x2200
	ds_read_b64_tr_b16 v[194:195], v143 offset:0x2a00
	v_max3_f32 v112, v112, v36, v37
	v_max3_f32 v112, v112, v38, v39
	v_max3_f32 v112, v112, v40, v41
	v_max3_f32 v112, v112, v42, v43
	v_max3_f32 v112, v112, v44, v45
	v_mfma_f32_32x32x16_bf16 v[0:15], v[136:139], v[196:199], v[0:15]
	ds_read_b64_tr_b16 v[196:197], v143 offset:0x3200
	ds_read_b64_tr_b16 v[198:199], v143 offset:0x3a00
	v_max3_f32 v112, v112, v46, v47
	v_mov_b32_e32 v113, v112
	s_nop 1
	v_permlane32_swap_b32_e32 v112, v113
	v_max_f32_e32 v112, v112, v113
	v_cmp_ge_f32_e32 vcc, s80, v112
	s_cmp_eq_u64 vcc, exec
	s_cbranch_scc0 .Lmy_rare_a2
	v_mov_b32_e32 v117, 1.0
.Lmy_join_a2:
	v_cmp_gt_f32_e32 vcc, 1.0, v117
	s_waitcnt lgkmcnt(0)
	v_mfma_f32_32x32x16_bf16 v[16:31], v[200:203], v[184:187], v[16:31]
	v_exp_f32_e32 v126, v48
	v_exp_f32_e32 v160, v49
	v_exp_f32_e32 v127, v50
	v_exp_f32_e32 v161, v51
	v_exp_f32_e32 v158, v52
	v_exp_f32_e32 v162, v53
	v_exp_f32_e32 v159, v54
	v_exp_f32_e32 v163, v55
	v_exp_f32_e32 v118, v56
	v_mfma_f32_32x32x16_bf16 v[16:31], v[226:229], v[188:191], v[16:31]
	v_exp_f32_e32 v121, v57
	v_exp_f32_e32 v119, v58
	v_exp_f32_e32 v122, v59
	v_exp_f32_e32 v120, v60
	v_exp_f32_e32 v123, v61
	v_exp_f32_e32 v124, v62
	v_exp_f32_e32 v125, v63
	v_exp_f32_e32 v114, v32
	v_exp_f32_e32 v115, v33
	v_mfma_f32_32x32x16_bf16 v[16:31], v[230:233], v[192:195], v[16:31]
	v_exp_f32_e32 v112, v34
	v_exp_f32_e32 v113, v35
	v_exp_f32_e32 v108, v36
	v_exp_f32_e32 v109, v37
	v_exp_f32_e32 v104, v38
	v_exp_f32_e32 v105, v39
	v_exp_f32_e32 v102, v40
	v_exp_f32_e32 v103, v41
	v_exp_f32_e32 v110, v42
	v_mfma_f32_32x32x16_bf16 v[16:31], v[136:139], v[196:199], v[16:31]
	v_exp_f32_e32 v111, v43
	v_exp_f32_e32 v106, v44
	v_exp_f32_e32 v107, v45
	v_exp_f32_e32 v101, v47
	v_exp_f32_e32 v100, v46
	v_add_f32_e32 v32, v155, v156
	v_fmac_f32_e32 v32, v154, v142
	v_add_f32_e32 v142, v164, v165
	v_fmac_f32_e32 v142, v32, v157
	s_cbranch_vccz .LBB0_310
	s_and_saveexec_b64 s[12:13], s[4:5]
	ds_write_b32 v141, v117 offset:128
	s_or_b64 exec, exec, s[12:13]
	s_waitcnt lgkmcnt(0)
	ds_read_b128 v[184:187], v129 offset:224
	ds_read_b128 v[188:191], v129 offset:192
	ds_read_b128 v[192:195], v129 offset:160
	ds_read_b128 v[196:199], v129 offset:128
	s_waitcnt lgkmcnt(3)
	v_pk_mul_f32 v[14:15], v[14:15], v[186:187]
	s_waitcnt lgkmcnt(2)
	v_pk_mul_f32 v[10:11], v[10:11], v[190:191]
	s_waitcnt lgkmcnt(1)
	v_pk_mul_f32 v[6:7], v[6:7], v[194:195]
	s_waitcnt lgkmcnt(0)
	v_pk_mul_f32 v[2:3], v[2:3], v[198:199]
	v_pk_mul_f32 v[12:13], v[12:13], v[184:185]
	v_pk_mul_f32 v[8:9], v[8:9], v[188:189]
	v_pk_mul_f32 v[4:5], v[4:5], v[192:193]
	v_pk_mul_f32 v[0:1], v[0:1], v[196:197]
	v_pk_mul_f32 v[30:31], v[30:31], v[186:187]
	v_pk_mul_f32 v[26:27], v[26:27], v[190:191]
	v_pk_mul_f32 v[22:23], v[22:23], v[194:195]
	v_pk_mul_f32 v[18:19], v[18:19], v[198:199]
	v_pk_mul_f32 v[28:29], v[28:29], v[184:185]
	v_pk_mul_f32 v[24:25], v[24:25], v[188:189]
	v_pk_mul_f32 v[20:21], v[20:21], v[192:193]
	v_pk_mul_f32 v[16:17], v[16:17], v[196:197]

; #define SBAR() __builtin_amdgcn_sched_barrier(0)
; #define SLOAD(i, j) do { const long kr_ = KROW(j); sr_[i].vs0 = ld8(Vp + (kr_ + sr) * ldv + sc); sr_[i].ks0 = ld8(Kp + (kr_ + sr) * ldk + sc); \
;     if (DQK == 96) sr_[i].ks1 = ld8(Kp + (kr_ + sr2) * ldk + sc2); } while (0)
; #define BIAS(P0, P1, j) do { if (MODE == 1) { SBAR(); if ((j) >= nA) na_bias(P0, P1, na, rs0 + (j) - nA, hi); SBAR(); } } while (0)
; template <int DQK> __device__ __forceinline__ void partialSM(f32x16& p0, f32x16& p1, float& m_reg, float& mn, float& alpha) {
;     ...
;   if (__builtin_expect(__all(pmax - m_reg <= THR / SCALE), 1)) { mn = m_reg; alpha = 1.f; }
;   else { mn = fmaxf(m_reg, pmax); alpha = __builtin_amdgcn_exp2f((m_reg - mn) * C); m_reg = mn; }
; template <int DQK, int MODE, int ldq, int ldk, int ldv> ...
;     ...
;   for (int j = 1; j + 1 < NT; j += 2) {
;     SBAR(); qkt<DQK>(pB0, pB1, K_lds + SHM_K, qr, r32, hi);
;     finishSM(pA0, pA1, alA, l_reg, pa0, pa1, pa2, pa3); SBAR();
;     SLOAD(SO, j + 2); SBAR();
;     pv_d0(o, vb0, pa0, pa1, pa2, pa3); BIAS(pB0, pB1, j); partialSM<DQK>(pB0, pB1, m_reg, mnB, alB);
.Lmy_rare_a1:
	v_max_f32_e32 v113, 0, v112
	v_sub_f32_e32 v32, v32, v113
	v_sub_f32_e32 v33, v33, v113
	v_sub_f32_e32 v34, v34, v113
	v_sub_f32_e32 v35, v35, v113
	v_sub_f32_e32 v36, v36, v113
	v_sub_f32_e32 v37, v37, v113
	v_sub_f32_e32 v38, v38, v113
	v_sub_f32_e32 v39, v39, v113
	v_sub_f32_e32 v40, v40, v113
	v_sub_f32_e32 v41, v41, v113
	v_sub_f32_e32 v42, v42, v113
	v_sub_f32_e32 v43, v43, v113
	v_sub_f32_e32 v44, v44, v113
	v_sub_f32_e32 v45, v45, v113
	v_sub_f32_e32 v46, v46, v113
	v_sub_f32_e32 v47, v47, v113
	v_sub_f32_e32 v48, v48, v113
	v_sub_f32_e32 v49, v49, v113
	v_sub_f32_e32 v50, v50, v113
	v_sub_f32_e32 v51, v51, v113
	v_sub_f32_e32 v52, v52, v113
	v_sub_f32_e32 v53, v53, v113
	v_sub_f32_e32 v54, v54, v113
	v_sub_f32_e32 v55, v55, v113
	v_sub_f32_e32 v56, v56, v113
	v_sub_f32_e32 v57, v57, v113
	v_sub_f32_e32 v58, v58, v113
	v_sub_f32_e32 v59, v59, v113
	v_sub_f32_e32 v60, v60, v113
	v_sub_f32_e32 v61, v61, v113
	v_sub_f32_e32 v62, v62, v113
	v_sub_f32_e32 v63, v63, v113
	v_sub_f32_e32 v210, v210, v113
	v_sub_f32_e32 v211, v211, v113
	v_sub_f32_e32 v212, v212, v113
	v_sub_f32_e32 v213, v213, v113
	v_sub_f32_e32 v214, v214, v113
	v_sub_f32_e32 v215, v215, v113
	v_sub_f32_e32 v216, v216, v113
	v_sub_f32_e32 v217, v217, v113
	v_sub_f32_e32 v218, v218, v113
	v_sub_f32_e32 v219, v219, v113
	v_sub_f32_e32 v220, v220, v113
	v_sub_f32_e32 v221, v221, v113
	v_sub_f32_e32 v222, v222, v113
	v_sub_f32_e32 v223, v223, v113
	v_sub_f32_e32 v224, v224, v113
	v_sub_f32_e32 v225, v225, v113
	v_sub_f32_e32 v113, 0, v113
	v_exp_f32_e32 v157, v113
	s_branch .Lmy_join_a1
.Lmy_rare_a2:
	v_max_f32_e32 v113, 0, v112
	v_sub_f32_e32 v32, v32, v113
	v_sub_f32_e32 v33, v33, v113
	v_sub_f32_e32 v34, v34, v113
	v_sub_f32_e32 v35, v35, v113
	v_sub_f32_e32 v36, v36, v113
	v_sub_f32_e32 v37, v37, v113
	v_sub_f32_e32 v38, v38, v113
	v_sub_f32_e32 v39, v39, v113
	v_sub_f32_e32 v40, v40, v113
	v_sub_f32_e32 v41, v41, v113
	v_sub_f32_e32 v42, v42, v113
	v_sub_f32_e32 v43, v43, v113
	v_sub_f32_e32 v44, v44, v113
	v_sub_f32_e32 v45, v45, v113
	v_sub_f32_e32 v46, v46, v113
	v_sub_f32_e32 v47, v47, v113
	v_sub_f32_e32 v48, v48, v113
	v_sub_f32_e32 v49, v49, v113
	v_sub_f32_e32 v50, v50, v113
	v_sub_f32_e32 v51, v51, v113
	v_sub_f32_e32 v52, v52, v113
	v_sub_f32_e32 v53, v53, v113
	v_sub_f32_e32 v54, v54, v113
	v_sub_f32_e32 v55, v55, v113
	v_sub_f32_e32 v56, v56, v113
	v_sub_f32_e32 v57, v57, v113
	v_sub_f32_e32 v58, v58, v113
	v_sub_f32_e32 v59, v59, v113
	v_sub_f32_e32 v60, v60, v113
	v_sub_f32_e32 v61, v61, v113
	v_sub_f32_e32 v62, v62, v113
	v_sub_f32_e32 v63, v63, v113
	v_sub_f32_e32 v210, v210, v113
	v_sub_f32_e32 v211, v211, v113
	v_sub_f32_e32 v212, v212, v113
	v_sub_f32_e32 v213, v213, v113
	v_sub_f32_e32 v214, v214, v113
	v_sub_f32_e32 v215, v215, v113
	v_sub_f32_e32 v216, v216, v113
	v_sub_f32_e32 v217, v217, v113
	v_sub_f32_e32 v218, v218, v113
	v_sub_f32_e32 v219, v219, v113
	v_sub_f32_e32 v220, v220, v113
	v_sub_f32_e32 v221, v221, v113
	v_sub_f32_e32 v222, v222, v113
	v_sub_f32_e32 v223, v223, v113
	v_sub_f32_e32 v224, v224, v113
	v_sub_f32_e32 v225, v225, v113
	v_sub_f32_e32 v113, 0, v113
	v_exp_f32_e32 v117, v113
	s_branch .Lmy_join_a2
	.p2align 8
.Lmy_h1B:
	s_waitcnt vmcnt(0)
	ds_write_b128 v146, v[88:91] offset:32768
	ds_write_b128 v145, v[92:95] offset:16384
	v_mov_b32_e32 v117, v114
	v_mov_b32_e32 v157, v115
	v_mov_b32_e32 v164, v112
	v_add_f32_e32 v112, 0, v126
	v_add_f32_e32 v112, v160, v112
	v_add_f32_e32 v112, v127, v112
	v_add_f32_e32 v112, v161, v112
	v_add_f32_e32 v112, v158, v112
	v_add_f32_e32 v112, v162, v112
	v_add_f32_e32 v112, v159, v112
	v_add_f32_e32 v112, v163, v112
	v_add_f32_e32 v112, v118, v112
	v_add_f32_e32 v112, v121, v112
	v_add_f32_e32 v112, v119, v112
	v_add_f32_e32 v112, v122, v112
	v_add_f32_e32 v112, v120, v112
	v_add_f32_e32 v112, v123, v112
	v_add_f32_e32 v112, v124, v112
	v_mov_b32_e32 v165, v113
	v_add_f32_e32 v112, v125, v112
	v_add_f32_e32 v112, v117, v112
	v_add_f32_e32 v112, v157, v112
	v_add_f32_e32 v112, v164, v112
	v_add_f32_e32 v112, v165, v112
	v_add_f32_e32 v112, v108, v112
	v_add_f32_e32 v112, v109, v112
	v_add_f32_e32 v112, v104, v112
	v_add_f32_e32 v112, v105, v112
	v_add_f32_e32 v112, v102, v112
	v_add_f32_e32 v112, v103, v112
	v_add_f32_e32 v112, v110, v112
	v_add_f32_e32 v112, v111, v112
	v_add_f32_e32 v112, v106, v112
	v_add_f32_e32 v112, v107, v112
	v_add_f32_e32 v112, v100, v112
	v_add_f32_e32 v155, v101, v112
	v_mov_b32_e32 v156, v155
	v_cvt_pk_bf16_f32 v200, v126, v160
	v_cvt_pk_bf16_f32 v201, v127, v161
	v_cvt_pk_bf16_f32 v202, v158, v162
	s_nop 1
	v_permlane32_swap_b32_e32 v155, v156
	v_cvt_pk_bf16_f32 v203, v159, v163
	v_permlane32_swap_b32_e32 v200, v202
	v_cvt_pk_bf16_f32 v226, v118, v121
	v_cvt_pk_bf16_f32 v227, v119, v122
	v_cvt_pk_bf16_f32 v228, v120, v123
	v_cvt_pk_bf16_f32 v229, v124, v125
	v_cvt_pk_bf16_f32 v230, v117, v157
	v_cvt_pk_bf16_f32 v231, v164, v165
	v_cvt_pk_bf16_f32 v232, v108, v109
	v_cvt_pk_bf16_f32 v233, v104, v105
	v_cvt_pk_bf16_f32 v136, v102, v103
	v_cvt_pk_bf16_f32 v137, v110, v111
	v_cvt_pk_bf16_f32 v138, v106, v107
	v_cvt_pk_bf16_f32 v139, v100, v101
	v_permlane32_swap_b32_e32 v201, v203
	v_permlane32_swap_b32_e32 v226, v228
	v_permlane32_swap_b32_e32 v227, v229
	v_permlane32_swap_b32_e32 v230, v232
	v_permlane32_swap_b32_e32 v231, v233
	v_permlane32_swap_b32_e32 v136, v138
	v_permlane32_swap_b32_e32 v137, v139
	s_cmpk_lt_u32 s25, 0x7e
	s_cselect_b32 s0, 0, 0xffffff80
	s_cselect_b32 s1, s10, s24
	s_add_i32 s0, s0, s11
	s_lshl_b32 s0, s0, 6
	s_add_i32 s0, s0, s1
	s_sub_i32 s0, s0, 64
	s_ashr_i32 s1, s0, 31
	s_cmpk_lt_u32 s25, 0x7f
	s_cselect_b32 s98, 0, 0xffffff80
	s_cselect_b32 s99, s10, s24
	s_add_i32 s98, s98, s11
	s_lshl_b32 s98, s98, 6
	s_add_i32 s98, s98, s99
	s_addk_i32 s98, 0xff80
	s_ashr_i32 s99, s98, 31
	s_mul_i32 s1, s0, 0x300
	s_add_u32 s12, s18, s1
	s_addc_u32 s13, s19, 0
	s_lshl_b32 s98, s98, 9
	s_add_u32 s98, s20, s98
	s_addc_u32 s99, s21, 0
	global_load_dwordx4 v[100:103], v134, s[12:13]
	global_load_dwordx4 v[108:111], v135, s[98:99]
	ds_read_b64_tr_b16 v[184:185], v144 offset:0
	ds_read_b64_tr_b16 v[186:187], v144 offset:0x800
	ds_read_b64_tr_b16 v[188:189], v144 offset:0x1000
	ds_read_b64_tr_b16 v[190:191], v144 offset:0x1800
	ds_read_b64_tr_b16 v[192:193], v144 offset:0x2000
	ds_read_b64_tr_b16 v[194:195], v144 offset:0x2800
	ds_read_b64_tr_b16 v[196:197], v144 offset:0x3000
	ds_read_b64_tr_b16 v[198:199], v144 offset:0x3800
	s_waitcnt lgkmcnt(0)
; #define SWRITE(b, i) do { *(bf16x8*)(V_lds + (b) * SHM_V + vst0) = sr_[i].vs0; *(bf16x8*)(K_lds + (b) * SHM_K + kst0) = sr_[i].ks0; \
;     if (DQK == 96) *(bf16x8*)(K_lds + (b) * SHM_K + kst1) = sr_[i].ks1; } while (0)
; #define RESC(a) do { if (__any((a) < 1.f)) { if (hi == 0) al_l[r32] = (a); asm volatile("s_waitcnt lgkmcnt(0)" ::: "memory"); \
;     _Pragma("unroll") for (int d = 0; d < 2; ++d) _Pragma("unroll") for (int r = 0; r < 16; ++r) o[d][r] *= al_l[crow(r, hi)]; } } while (0)
; #define BIAS(P0, P1, j) do { if (MODE == 1) { SBAR(); if ((j) >= nA) na_bias(P0, P1, na, rs0 + (j) - nA, hi); SBAR(); } } while (0)
; template <int DQK, int MODE, int ldq, int ldk, int ldv> ...
;     ...
;     pv_d0(o, vb0, pa0, pa1, pa2, pa3); BIAS(pB0, pB1, j); partialSM<DQK>(pB0, pB1, m_reg, mnB, alB);
;     __syncthreads(); SWRITE(0, SE);
;     RESC(alB); __syncthreads();
	s_nop 0
	v_mfma_f32_32x32x16_bf16 v[0:15], v[200:203], v[184:187], v[0:15]
	ds_read_b64_tr_b16 v[184:185], v144 offset:0x200
	ds_read_b64_tr_b16 v[186:187], v144 offset:0xa00
	v_mfma_f32_32x32x16_bf16 v[0:15], v[226:229], v[188:191], v[0:15]
	ds_read_b64_tr_b16 v[188:189], v144 offset:0x1200
	ds_read_b64_tr_b16 v[190:191], v144 offset:0x1a00
	v_mfma_f32_32x32x16_bf16 v[0:15], v[230:233], v[192:195], v[0:15]
	ds_read_b64_tr_b16 v[192:193], v144 offset:0x2200
	ds_read_b64_tr_b16 v[194:195], v144 offset:0x2a00
	v_mfma_f32_32x32x16_bf16 v[0:15], v[136:139], v[196:199], v[0:15]
	ds_read_b64_tr_b16 v[196:197], v144 offset:0x3200
	ds_read_b64_tr_b16 v[198:199], v144 offset:0x3a00
	s_waitcnt lgkmcnt(0)
	v_mfma_f32_32x32x16_bf16 v[16:31], v[200:203], v[184:187], v[16:31]
	v_mfma_f32_32x32x16_bf16 v[16:31], v[226:229], v[188:191], v[16:31]
	v_mfma_f32_32x32x16_bf16 v[16:31], v[230:233], v[192:195], v[16:31]
	v_mfma_f32_32x32x16_bf16 v[16:31], v[136:139], v[196:199], v[16:31]
	ds_read_b128 v[32:35], v148 offset:49152
	ds_read_b128 v[36:39], v148 offset:57344
	ds_read_b128 v[164:167], v152 offset:49152
	ds_read_b128 v[168:171], v152 offset:57344
	s_waitcnt lgkmcnt(3)
	v_mfma_f32_32x32x16_bf16 v[48:63], v[32:35], v[84:87], v[210:225]
	s_waitcnt lgkmcnt(2)
	v_mfma_f32_32x32x16_bf16 v[32:47], v[36:39], v[84:87], v[210:225]
	s_waitcnt lgkmcnt(1)
	v_mfma_f32_32x32x16_bf16 v[48:63], v[164:167], v[80:83], v[48:63]
	s_waitcnt lgkmcnt(0)
	v_mfma_f32_32x32x16_bf16 v[32:47], v[168:171], v[80:83], v[32:47]
	ds_read_b128 v[164:167], v151 offset:49152
	ds_read_b128 v[168:171], v151 offset:57344
	s_waitcnt lgkmcnt(1)
	v_mfma_f32_32x32x16_bf16 v[48:63], v[164:167], v[76:79], v[48:63]
	s_waitcnt lgkmcnt(0)
	v_mfma_f32_32x32x16_bf16 v[32:47], v[168:171], v[76:79], v[32:47]
	ds_read_b128 v[164:167], v149 offset:49152
	ds_read_b128 v[168:171], v149 offset:57344
	s_waitcnt lgkmcnt(1)
	v_mfma_f32_32x32x16_bf16 v[48:63], v[164:167], v[72:75], v[48:63]
	s_waitcnt lgkmcnt(0)
	v_mfma_f32_32x32x16_bf16 v[32:47], v[168:171], v[72:75], v[32:47]
	ds_read_b128 v[164:167], v150 offset:49152
	ds_read_b128 v[168:171], v150 offset:57344
	s_waitcnt lgkmcnt(1)
	v_mfma_f32_32x32x16_bf16 v[48:63], v[164:167], v[68:71], v[48:63]
	s_waitcnt lgkmcnt(0)
	v_mfma_f32_32x32x16_bf16 v[32:47], v[168:171], v[68:71], v[32:47]
	ds_read_b128 v[164:167], v153 offset:49152
	ds_read_b128 v[168:171], v153 offset:57344
	s_waitcnt lgkmcnt(1)
	v_mfma_f32_32x32x16_bf16 v[48:63], v[164:167], v[64:67], v[48:63]
	s_waitcnt lgkmcnt(0)
	v_mfma_f32_32x32x16_bf16 v[32:47], v[168:171], v[64:67], v[32:47]
	s_nop 7
	s_nop 4
	v_max_f32_e32 v112, v48, v49
	v_max3_f32 v112, v112, v50, v51
	v_max3_f32 v112, v112, v52, v53
	v_max3_f32 v112, v112, v54, v55
	v_max3_f32 v112, v112, v56, v57
	v_max3_f32 v112, v112, v58, v59
	v_max3_f32 v112, v112, v60, v61
	v_max3_f32 v112, v112, v62, v63
	v_max3_f32 v112, v112, v32, v33
	v_max3_f32 v112, v112, v34, v35
	v_max3_f32 v112, v112, v36, v37
	v_max3_f32 v112, v112, v38, v39
	v_max3_f32 v112, v112, v40, v41
	v_max3_f32 v112, v112, v42, v43
	v_max3_f32 v112, v112, v44, v45
	v_max3_f32 v112, v112, v46, v47
	v_mov_b32_e32 v113, v112
	s_nop 1
	v_permlane32_swap_b32_e32 v112, v113
	v_max_f32_e32 v112, v112, v113
	v_cmp_ge_f32_e32 vcc, s80, v112
	s_cmp_eq_u64 vcc, exec
	s_cbranch_scc0 .Lmy_rare_b1
	v_mov_b32_e32 v157, 1.0
.Lmy_join_b1:
	v_cmp_gt_f32_e32 vcc, 1.0, v157
	v_exp_f32_e32 v112, v48
	v_exp_f32_e32 v127, v49
	v_exp_f32_e32 v113, v50
	v_exp_f32_e32 v126, v51
	v_exp_f32_e32 v114, v52
	v_exp_f32_e32 v125, v53
	v_exp_f32_e32 v115, v54
	v_exp_f32_e32 v124, v55
	v_exp_f32_e32 v116, v56
	v_exp_f32_e32 v123, v57
	v_exp_f32_e32 v117, v58
	v_exp_f32_e32 v122, v59
	v_exp_f32_e32 v118, v60
	v_exp_f32_e32 v121, v61
	v_exp_f32_e32 v119, v62
	v_exp_f32_e32 v120, v63
	v_exp_f32_e32 v164, v42
	v_exp_f32_e32 v165, v43
	v_exp_f32_e32 v167, v32
	v_exp_f32_e32 v168, v33
	v_exp_f32_e32 v169, v34
	v_exp_f32_e32 v170, v35
	v_exp_f32_e32 v171, v36
	v_exp_f32_e32 v172, v37
	v_exp_f32_e32 v160, v38
	v_exp_f32_e32 v161, v39
	v_exp_f32_e32 v162, v40
	v_exp_f32_e32 v163, v41
	v_exp_f32_e32 v166, v44
	v_exp_f32_e32 v173, v45
	v_exp_f32_e32 v174, v46
	v_exp_f32_e32 v159, v47
	s_cbranch_vccz .Lmy_h1B_304
	s_and_saveexec_b64 s[12:13], s[4:5]
	ds_write_b32 v141, v157 offset:128
	s_or_b64 exec, exec, s[12:13]
	s_waitcnt lgkmcnt(0)
	ds_read_b128 v[184:187], v129 offset:224
	ds_read_b128 v[188:191], v129 offset:192
	ds_read_b128 v[192:195], v129 offset:160
	ds_read_b128 v[196:199], v129 offset:128
	s_waitcnt lgkmcnt(3)
	v_pk_mul_f32 v[14:15], v[14:15], v[186:187]
	s_waitcnt lgkmcnt(2)
	v_pk_mul_f32 v[10:11], v[10:11], v[190:191]
	s_waitcnt lgkmcnt(1)
	v_pk_mul_f32 v[6:7], v[6:7], v[194:195]
	s_waitcnt lgkmcnt(0)
	v_pk_mul_f32 v[2:3], v[2:3], v[198:199]
	v_pk_mul_f32 v[12:13], v[12:13], v[184:185]
	v_pk_mul_f32 v[8:9], v[8:9], v[188:189]
	v_pk_mul_f32 v[4:5], v[4:5], v[192:193]
	v_pk_mul_f32 v[0:1], v[0:1], v[196:197]
	v_pk_mul_f32 v[30:31], v[30:31], v[186:187]
	v_pk_mul_f32 v[26:27], v[26:27], v[190:191]
	v_pk_mul_f32 v[22:23], v[22:23], v[194:195]
	v_pk_mul_f32 v[18:19], v[18:19], v[198:199]
	v_pk_mul_f32 v[28:29], v[28:29], v[184:185]
	v_pk_mul_f32 v[24:25], v[24:25], v[188:189]
	v_pk_mul_f32 v[20:21], v[20:21], v[192:193]
	v_pk_mul_f32 v[16:17], v[16:17], v[196:197]
; #define SBAR() __builtin_amdgcn_sched_barrier(0)
; #define SLOAD(i, j) do { const long kr_ = KROW(j); sr_[i].vs0 = ld8(Vp + (kr_ + sr) * ldv + sc); sr_[i].ks0 = ld8(Kp + (kr_ + sr) * ldk + sc); \
;     if (DQK == 96) sr_[i].ks1 = ld8(Kp + (kr_ + sr2) * ldk + sc2); } while (0)
; #define SWRITE(b, i) do { *(bf16x8*)(V_lds + (b) * SHM_V + vst0) = sr_[i].vs0; *(bf16x8*)(K_lds + (b) * SHM_K + kst0) = sr_[i].ks0; \
;     if (DQK == 96) *(bf16x8*)(K_lds + (b) * SHM_K + kst1) = sr_[i].ks1; } while (0)
; #define RESC(a) do { if (__any((a) < 1.f)) { if (hi == 0) al_l[r32] = (a); asm volatile("s_waitcnt lgkmcnt(0)" ::: "memory"); \
;     _Pragma("unroll") for (int d = 0; d < 2; ++d) _Pragma("unroll") for (int r = 0; r < 16; ++r) o[d][r] *= al_l[crow(r, hi)]; } } while (0)
; template <int DQK, int MODE, int ldq, int ldk, int ldv> ...
;     ...
;     __syncthreads(); SWRITE(0, SE);
;     RESC(alB); __syncthreads();
;     SBAR(); qkt<DQK>(pA0, pA1, K_lds, qr, r32, hi);
;     finishSM(pB0, pB1, alB, l_reg, pa0, pa1, pa2, pa3); SBAR();
;     if (j + 3 < NT) SLOAD(SE, j + 3); SBAR();
.Lmy_h1B_304:
	s_waitcnt lgkmcnt(0)
	s_barrier
	s_waitcnt vmcnt(0)
	ds_write_b128 v146, v[100:103] offset:49152
	ds_write_b128 v145, v[108:111]
	v_mov_b32_e32 v175, v164
	v_add_f32_e32 v164, 0, v112
	v_add_f32_e32 v164, v127, v164
	v_add_f32_e32 v164, v113, v164
	v_add_f32_e32 v164, v126, v164
	v_add_f32_e32 v164, v114, v164
	v_add_f32_e32 v164, v125, v164
	v_add_f32_e32 v164, v115, v164
	v_add_f32_e32 v164, v124, v164
	v_add_f32_e32 v164, v116, v164
	v_add_f32_e32 v164, v123, v164
	v_add_f32_e32 v164, v117, v164
	v_add_f32_e32 v164, v122, v164
	v_add_f32_e32 v164, v118, v164
	v_add_f32_e32 v164, v121, v164
	v_add_f32_e32 v164, v119, v164
	v_add_f32_e32 v164, v120, v164
	v_add_f32_e32 v164, v167, v164
	v_add_f32_e32 v164, v168, v164
	v_add_f32_e32 v164, v169, v164
	v_add_f32_e32 v164, v170, v164
	v_add_f32_e32 v164, v171, v164
	v_add_f32_e32 v164, v172, v164
	v_add_f32_e32 v164, v160, v164
	v_add_f32_e32 v164, v161, v164
	v_add_f32_e32 v164, v162, v164
	v_add_f32_e32 v164, v163, v164
	v_add_f32_e32 v164, v175, v164
	v_cvt_pk_bf16_f32 v200, v112, v127
	v_cvt_pk_bf16_f32 v201, v113, v126
	v_cvt_pk_bf16_f32 v202, v114, v125
	v_cvt_pk_bf16_f32 v203, v115, v124
	v_cvt_pk_bf16_f32 v226, v116, v123
	v_cvt_pk_bf16_f32 v227, v117, v122
	v_mov_b32_e32 v176, v165
	v_cvt_pk_bf16_f32 v228, v118, v121
	v_cvt_pk_bf16_f32 v229, v119, v120
	v_cvt_pk_bf16_f32 v230, v167, v168
	v_cvt_pk_bf16_f32 v231, v169, v170
	v_cvt_pk_bf16_f32 v232, v171, v172
	s_nop 0
	v_add_f32_e32 v164, v176, v164
	v_add_f32_e32 v164, v166, v164
	v_add_f32_e32 v164, v173, v164
	v_add_f32_e32 v164, v174, v164
	v_add_f32_e32 v164, v159, v164
	v_mov_b32_e32 v165, v164
	v_cvt_pk_bf16_f32 v233, v160, v161
	v_cvt_pk_bf16_f32 v136, v162, v163
	v_cvt_pk_bf16_f32 v137, v175, v176
	v_cvt_pk_bf16_f32 v138, v166, v173
	v_cvt_pk_bf16_f32 v139, v174, v159
	s_nop 1
	v_permlane32_swap_b32_e32 v164, v165
	v_permlane32_swap_b32_e32 v200, v202
	v_permlane32_swap_b32_e32 v201, v203
	v_permlane32_swap_b32_e32 v226, v228
	v_permlane32_swap_b32_e32 v227, v229
	v_permlane32_swap_b32_e32 v230, v232
	v_permlane32_swap_b32_e32 v231, v233
	v_permlane32_swap_b32_e32 v136, v138
	v_permlane32_swap_b32_e32 v137, v139
	s_cmpk_lt_u32 s25, 0x7e
	s_cselect_b32 s98, 0, 0xffffff80
	s_cselect_b32 s99, s10, s24
	s_add_i32 s98, s98, s11
	s_lshl_b32 s98, s98, 6
	s_add_i32 s98, s98, s99
	s_sub_i32 s98, s98, 64
	s_ashr_i32 s99, s98, 31
	s_lshl_b32 s98, s98, 9
	s_add_u32 s98, s20, s98
	s_addc_u32 s99, s21, 0
	global_load_dwordx4 v[92:95], v135, s[98:99]
	s_cmpk_gt_u32 s25, 0x80
	s_cbranch_scc1 .Lmy_h2B_306
	s_cmpk_lt_u32 s25, 0x7d
	s_cselect_b32 s0, 0, 0xffffff80
	s_cselect_b32 s1, s10, s24
	s_add_i32 s0, s0, s11
	s_lshl_b32 s0, s0, 6
	s_add_i32 s0, s0, s1
	s_ashr_i32 s1, s0, 31
	s_mul_i32 s1, s0, 0x300
	s_add_u32 s12, s18, s1
	s_addc_u32 s13, s19, 0
	global_load_dwordx4 v[88:91], v134, s[12:13]
; #define SWRITE(b, i) do { *(bf16x8*)(V_lds + (b) * SHM_V + vst0) = sr_[i].vs0; *(bf16x8*)(K_lds + (b) * SHM_K + kst0) = sr_[i].ks0; \
;     if (DQK == 96) *(bf16x8*)(K_lds + (b) * SHM_K + kst1) = sr_[i].ks1; } while (0)
; #define RESC(a) do { if (__any((a) < 1.f)) { if (hi == 0) al_l[r32] = (a); asm volatile("s_waitcnt lgkmcnt(0)" ::: "memory"); \
;     _Pragma("unroll") for (int d = 0; d < 2; ++d) _Pragma("unroll") for (int r = 0; r < 16; ++r) o[d][r] *= al_l[crow(r, hi)]; } } while (0)
; #define BIAS(P0, P1, j) do { if (MODE == 1) { SBAR(); if ((j) >= nA) na_bias(P0, P1, na, rs0 + (j) - nA, hi); SBAR(); } } while (0)
; template <int DQK, int MODE, int ldq, int ldk, int ldv> ...
;     ...
;     pv_d0(o, vb0 + (int)SHM_V, pa0, pa1, pa2, pa3); BIAS(pA0, pA1, j + 1); partialSM<DQK>(pA0, pA1, m_reg, mnA, alA);
;     __syncthreads(); SWRITE(1, SO);
;     RESC(alA); __syncthreads();
.Lmy_h2B_306:
	ds_read_b64_tr_b16 v[184:185], v143 offset:0
	ds_read_b64_tr_b16 v[186:187], v143 offset:0x800
	ds_read_b64_tr_b16 v[188:189], v143 offset:0x1000
	ds_read_b64_tr_b16 v[190:191], v143 offset:0x1800
	ds_read_b64_tr_b16 v[192:193], v143 offset:0x2000
	ds_read_b64_tr_b16 v[194:195], v143 offset:0x2800
	ds_read_b64_tr_b16 v[196:197], v143 offset:0x3000
	ds_read_b64_tr_b16 v[198:199], v143 offset:0x3800
	s_waitcnt lgkmcnt(0)
	s_nop 0
	v_mfma_f32_32x32x16_bf16 v[0:15], v[200:203], v[184:187], v[0:15]
	ds_read_b64_tr_b16 v[184:185], v143 offset:0x200
	ds_read_b64_tr_b16 v[186:187], v143 offset:0xa00
	v_mfma_f32_32x32x16_bf16 v[0:15], v[226:229], v[188:191], v[0:15]
	ds_read_b64_tr_b16 v[188:189], v143 offset:0x1200
	ds_read_b64_tr_b16 v[190:191], v143 offset:0x1a00
	v_mfma_f32_32x32x16_bf16 v[0:15], v[230:233], v[192:195], v[0:15]
	ds_read_b64_tr_b16 v[192:193], v143 offset:0x2200
	ds_read_b64_tr_b16 v[194:195], v143 offset:0x2a00
	v_mfma_f32_32x32x16_bf16 v[0:15], v[136:139], v[196:199], v[0:15]
	ds_read_b64_tr_b16 v[196:197], v143 offset:0x3200
	ds_read_b64_tr_b16 v[198:199], v143 offset:0x3a00
	s_waitcnt lgkmcnt(0)
	v_mfma_f32_32x32x16_bf16 v[16:31], v[200:203], v[184:187], v[16:31]
	v_mfma_f32_32x32x16_bf16 v[16:31], v[226:229], v[188:191], v[16:31]
	v_mfma_f32_32x32x16_bf16 v[16:31], v[230:233], v[192:195], v[16:31]
	v_mfma_f32_32x32x16_bf16 v[16:31], v[136:139], v[196:199], v[16:31]
	ds_read_b128 v[32:35], v148 offset:32768
	ds_read_b128 v[36:39], v148 offset:40960
	ds_read_b128 v[176:179], v152 offset:32768
	ds_read_b128 v[180:183], v152 offset:40960
	s_waitcnt lgkmcnt(3)
	v_mfma_f32_32x32x16_bf16 v[48:63], v[32:35], v[84:87], v[210:225]
	s_waitcnt lgkmcnt(2)
	v_mfma_f32_32x32x16_bf16 v[32:47], v[36:39], v[84:87], v[210:225]
	s_waitcnt lgkmcnt(1)
	v_mfma_f32_32x32x16_bf16 v[48:63], v[176:179], v[80:83], v[48:63]
	s_waitcnt lgkmcnt(0)
	v_mfma_f32_32x32x16_bf16 v[32:47], v[180:183], v[80:83], v[32:47]
	ds_read_b128 v[176:179], v151 offset:32768
	ds_read_b128 v[180:183], v151 offset:40960
	s_waitcnt lgkmcnt(1)
	v_mfma_f32_32x32x16_bf16 v[48:63], v[176:179], v[76:79], v[48:63]
	s_waitcnt lgkmcnt(0)
	v_mfma_f32_32x32x16_bf16 v[32:47], v[180:183], v[76:79], v[32:47]
	ds_read_b128 v[176:179], v149 offset:32768
	ds_read_b128 v[180:183], v149 offset:40960
	s_waitcnt lgkmcnt(1)
	v_mfma_f32_32x32x16_bf16 v[48:63], v[176:179], v[72:75], v[48:63]
	s_waitcnt lgkmcnt(0)
	v_mfma_f32_32x32x16_bf16 v[32:47], v[180:183], v[72:75], v[32:47]
	ds_read_b128 v[176:179], v150 offset:32768
	ds_read_b128 v[180:183], v150 offset:40960
	s_waitcnt lgkmcnt(1)
	v_mfma_f32_32x32x16_bf16 v[48:63], v[176:179], v[68:71], v[48:63]
	s_waitcnt lgkmcnt(0)
	v_mfma_f32_32x32x16_bf16 v[32:47], v[180:183], v[68:71], v[32:47]
	ds_read_b128 v[176:179], v153 offset:32768
	ds_read_b128 v[180:183], v153 offset:40960
	s_waitcnt lgkmcnt(1)
	v_mfma_f32_32x32x16_bf16 v[48:63], v[176:179], v[64:67], v[48:63]
	s_waitcnt lgkmcnt(0)
	v_mfma_f32_32x32x16_bf16 v[32:47], v[180:183], v[64:67], v[32:47]
	s_nop 7
	s_nop 4
	v_max_f32_e32 v112, v48, v49
	v_max3_f32 v112, v112, v50, v51
	v_max3_f32 v112, v112, v52, v53
	v_max3_f32 v112, v112, v54, v55
	v_max3_f32 v112, v112, v56, v57
	v_max3_f32 v112, v112, v58, v59
	v_max3_f32 v112, v112, v60, v61
	v_max3_f32 v112, v112, v62, v63
	v_max3_f32 v112, v112, v32, v33
	v_max3_f32 v112, v112, v34, v35
	v_max3_f32 v112, v112, v36, v37
	v_max3_f32 v112, v112, v38, v39
	v_max3_f32 v112, v112, v40, v41
	v_max3_f32 v112, v112, v42, v43
	v_max3_f32 v112, v112, v44, v45
	v_max3_f32 v112, v112, v46, v47
	v_mov_b32_e32 v113, v112
	s_nop 1
	v_permlane32_swap_b32_e32 v112, v113
	v_max_f32_e32 v112, v112, v113
	v_cmp_ge_f32_e32 vcc, s80, v112
	s_cmp_eq_u64 vcc, exec
	s_cbranch_scc0 .Lmy_rare_b2
	v_mov_b32_e32 v117, 1.0
.Lmy_join_b2:
	v_cmp_gt_f32_e32 vcc, 1.0, v117
	v_exp_f32_e32 v126, v48
	v_exp_f32_e32 v160, v49
	v_exp_f32_e32 v127, v50
	v_exp_f32_e32 v161, v51
	v_exp_f32_e32 v158, v52
	v_exp_f32_e32 v162, v53
	v_exp_f32_e32 v159, v54
	v_exp_f32_e32 v163, v55
	v_exp_f32_e32 v118, v56
	v_exp_f32_e32 v121, v57
	v_exp_f32_e32 v119, v58
	v_exp_f32_e32 v122, v59
	v_exp_f32_e32 v120, v60
	v_exp_f32_e32 v123, v61
	v_exp_f32_e32 v124, v62
	v_exp_f32_e32 v125, v63
	v_exp_f32_e32 v114, v32
	v_exp_f32_e32 v115, v33
	v_exp_f32_e32 v112, v34
	v_exp_f32_e32 v113, v35
	v_exp_f32_e32 v108, v36
	v_exp_f32_e32 v109, v37
	v_exp_f32_e32 v104, v38
	v_exp_f32_e32 v105, v39
	v_exp_f32_e32 v102, v40
	v_exp_f32_e32 v103, v41
	v_exp_f32_e32 v110, v42
	v_exp_f32_e32 v111, v43
	v_exp_f32_e32 v106, v44
	v_exp_f32_e32 v107, v45
	v_exp_f32_e32 v101, v47
	v_exp_f32_e32 v100, v46
	v_add_f32_e32 v32, v155, v156
	v_fmac_f32_e32 v32, v154, v142
	v_add_f32_e32 v142, v164, v165
	v_fmac_f32_e32 v142, v32, v157
	s_cbranch_vccz .Lmy_h2B_310
	s_and_saveexec_b64 s[12:13], s[4:5]
	ds_write_b32 v141, v117 offset:128
	s_or_b64 exec, exec, s[12:13]
	s_waitcnt lgkmcnt(0)
	ds_read_b128 v[184:187], v129 offset:224
	ds_read_b128 v[188:191], v129 offset:192
	ds_read_b128 v[192:195], v129 offset:160
	ds_read_b128 v[196:199], v129 offset:128
	s_waitcnt lgkmcnt(3)
	v_pk_mul_f32 v[14:15], v[14:15], v[186:187]
	s_waitcnt lgkmcnt(2)
	v_pk_mul_f32 v[10:11], v[10:11], v[190:191]
	s_waitcnt lgkmcnt(1)
	v_pk_mul_f32 v[6:7], v[6:7], v[194:195]
	s_waitcnt lgkmcnt(0)
	v_pk_mul_f32 v[2:3], v[2:3], v[198:199]
	v_pk_mul_f32 v[12:13], v[12:13], v[184:185]
	v_pk_mul_f32 v[8:9], v[8:9], v[188:189]
	v_pk_mul_f32 v[4:5], v[4:5], v[192:193]
	v_pk_mul_f32 v[0:1], v[0:1], v[196:197]
	v_pk_mul_f32 v[30:31], v[30:31], v[186:187]
	v_pk_mul_f32 v[26:27], v[26:27], v[190:191]
	v_pk_mul_f32 v[22:23], v[22:23], v[194:195]
	v_pk_mul_f32 v[18:19], v[18:19], v[198:199]
	v_pk_mul_f32 v[28:29], v[28:29], v[184:185]
	v_pk_mul_f32 v[24:25], v[24:25], v[188:189]
	v_pk_mul_f32 v[20:21], v[20:21], v[192:193]
	v_pk_mul_f32 v[16:17], v[16:17], v[196:197]

; #define SBAR() __builtin_amdgcn_sched_barrier(0)
; #define BIAS(P0, P1, j) do { if (MODE == 1) { SBAR(); if ((j) >= nA) na_bias(P0, P1, na, rs0 + (j) - nA, hi); SBAR(); } } while (0)
; template <int DQK, int MODE, int ldq, int ldk, int ldv> ...
;     ...
;   SBAR(); qkt<DQK>(pB0, pB1, K_lds + SHM_K, qr, r32, hi);
;   finishSM(pA0, pA1, alA, l_reg, pa0, pa1, pa2, pa3); SBAR();
;   pv_d0(o, vb0, pa0, pa1, pa2, pa3); BIAS(pB0, pB1, NT - 1); partialSM<DQK>(pB0, pB1, m_reg, mnB, alB);
.Lmy_rare_b2:
	v_max_f32_e32 v113, 0, v112
	v_sub_f32_e32 v32, v32, v113
	v_sub_f32_e32 v33, v33, v113
	v_sub_f32_e32 v34, v34, v113
	v_sub_f32_e32 v35, v35, v113
	v_sub_f32_e32 v36, v36, v113
	v_sub_f32_e32 v37, v37, v113
	v_sub_f32_e32 v38, v38, v113
	v_sub_f32_e32 v39, v39, v113
	v_sub_f32_e32 v40, v40, v113
	v_sub_f32_e32 v41, v41, v113
	v_sub_f32_e32 v42, v42, v113
	v_sub_f32_e32 v43, v43, v113
	v_sub_f32_e32 v44, v44, v113
	v_sub_f32_e32 v45, v45, v113
	v_sub_f32_e32 v46, v46, v113
	v_sub_f32_e32 v47, v47, v113
	v_sub_f32_e32 v48, v48, v113
	v_sub_f32_e32 v49, v49, v113
	v_sub_f32_e32 v50, v50, v113
	v_sub_f32_e32 v51, v51, v113
	v_sub_f32_e32 v52, v52, v113
	v_sub_f32_e32 v53, v53, v113
	v_sub_f32_e32 v54, v54, v113
	v_sub_f32_e32 v55, v55, v113
	v_sub_f32_e32 v56, v56, v113
	v_sub_f32_e32 v57, v57, v113
	v_sub_f32_e32 v58, v58, v113
	v_sub_f32_e32 v59, v59, v113
	v_sub_f32_e32 v60, v60, v113
	v_sub_f32_e32 v61, v61, v113
	v_sub_f32_e32 v62, v62, v113
	v_sub_f32_e32 v63, v63, v113
	v_sub_f32_e32 v210, v210, v113
	v_sub_f32_e32 v211, v211, v113
	v_sub_f32_e32 v212, v212, v113
	v_sub_f32_e32 v213, v213, v113
	v_sub_f32_e32 v214, v214, v113
	v_sub_f32_e32 v215, v215, v113
	v_sub_f32_e32 v216, v216, v113
	v_sub_f32_e32 v217, v217, v113
	v_sub_f32_e32 v218, v218, v113
	v_sub_f32_e32 v219, v219, v113
	v_sub_f32_e32 v220, v220, v113
	v_sub_f32_e32 v221, v221, v113
	v_sub_f32_e32 v222, v222, v113
	v_sub_f32_e32 v223, v223, v113
	v_sub_f32_e32 v224, v224, v113
	v_sub_f32_e32 v225, v225, v113
	v_sub_f32_e32 v113, 0, v113
	v_exp_f32_e32 v117, v113
	s_branch .Lmy_join_b2
.LBB0_312:
	v_sub_f32_e32 v116, 0, v210
	s_waitcnt vmcnt(0)
	ds_write_b128 v145, v[92:95] offset:16384
	ds_read_b128 v[32:35], v148 offset:49152
	ds_read_b128 v[36:39], v148 offset:57344
	s_waitcnt lgkmcnt(1)
	v_mfma_f32_32x32x16_bf16 v[48:63], v[32:35], v[84:87], 0
	s_waitcnt lgkmcnt(0)
	v_mfma_f32_32x32x16_bf16 v[32:47], v[36:39], v[84:87], 0
	ds_read_b128 v[84:87], v152 offset:49152
	ds_read_b128 v[88:91], v152 offset:57344
	s_waitcnt lgkmcnt(1)
	v_mfma_f32_32x32x16_bf16 v[48:63], v[84:87], v[80:83], v[48:63]
	s_waitcnt lgkmcnt(0)
	v_mfma_f32_32x32x16_bf16 v[32:47], v[88:91], v[80:83], v[32:47]
	ds_read_b128 v[80:83], v151 offset:49152
	ds_read_b128 v[84:87], v151 offset:57344
	v_mov_b32_e32 v88, v100
	v_mov_b32_e32 v89, v101
	s_waitcnt lgkmcnt(1)
	v_mfma_f32_32x32x16_bf16 v[48:63], v[80:83], v[76:79], v[48:63]
	s_waitcnt lgkmcnt(0)
	v_mfma_f32_32x32x16_bf16 v[32:47], v[84:87], v[76:79], v[32:47]
	ds_read_b128 v[76:79], v149 offset:49152
	ds_read_b128 v[80:83], v149 offset:57344
	v_mov_b32_e32 v84, v110
	v_mov_b32_e32 v85, v111
	v_mov_b32_e32 v86, v106
	v_mov_b32_e32 v87, v107
	s_waitcnt lgkmcnt(1)
	v_mfma_f32_32x32x16_bf16 v[48:63], v[76:79], v[72:75], v[48:63]
	s_waitcnt lgkmcnt(0)
	v_mfma_f32_32x32x16_bf16 v[32:47], v[80:83], v[72:75], v[32:47]
	ds_read_b128 v[72:75], v150 offset:49152
	ds_read_b128 v[76:79], v150 offset:57344
	v_mov_b32_e32 v80, v104
	v_mov_b32_e32 v81, v105
	v_mov_b32_e32 v82, v102
	v_mov_b32_e32 v83, v103
	s_waitcnt lgkmcnt(1)
	v_mfma_f32_32x32x16_bf16 v[48:63], v[72:75], v[68:71], v[48:63]
	s_waitcnt lgkmcnt(0)
	v_mfma_f32_32x32x16_bf16 v[32:47], v[76:79], v[68:71], v[32:47]
	ds_read_b128 v[68:71], v153 offset:49152
	ds_read_b128 v[72:75], v153 offset:57344
	v_mov_b32_e32 v76, v112
	v_mov_b32_e32 v77, v113
	v_mov_b32_e32 v78, v108
	v_mov_b32_e32 v79, v109
	s_waitcnt lgkmcnt(1)
	v_mfma_f32_32x32x16_bf16 v[48:63], v[68:71], v[64:67], v[48:63]
	s_waitcnt lgkmcnt(0)
	v_mfma_f32_32x32x16_bf16 v[32:47], v[72:75], v[64:67], v[32:47]
	v_add_f32_e32 v64, 0, v126
	v_add_f32_e32 v64, v160, v64
	v_add_f32_e32 v64, v127, v64
	v_add_f32_e32 v64, v161, v64
	v_add_f32_e32 v64, v158, v64
	v_add_f32_e32 v64, v162, v64
	v_add_f32_e32 v64, v159, v64
	v_add_f32_e32 v64, v163, v64
	v_add_f32_e32 v64, v118, v64
	v_add_f32_e32 v64, v121, v64
	v_add_f32_e32 v64, v119, v64
	v_add_f32_e32 v64, v122, v64
	v_mov_b32_e32 v74, v114
	v_add_f32_e32 v64, v120, v64
	v_mov_b32_e32 v75, v115
	v_add_f32_e32 v64, v123, v64
	v_add_f32_e32 v64, v124, v64
	v_add_f32_e32 v64, v125, v64
	v_add_f32_e32 v64, v74, v64
	v_add_f32_e32 v64, v75, v64
	v_add_f32_e32 v64, v76, v64
	v_add_f32_e32 v64, v77, v64
	v_add_f32_e32 v64, v78, v64
	v_add_f32_e32 v64, v79, v64
	v_add_f32_e32 v64, v80, v64
	v_add_f32_e32 v64, v81, v64
	v_add_f32_e32 v64, v82, v64
	v_add_f32_e32 v64, v83, v64
	v_add_f32_e32 v64, v84, v64
	v_add_f32_e32 v64, v85, v64
	v_add_f32_e32 v64, v86, v64
	v_add_f32_e32 v64, v87, v64
	v_add_f32_e32 v64, v88, v64
	v_add_f32_e32 v64, v89, v64
	v_mov_b32_e32 v65, v64
	v_cvt_pk_bf16_f32 v66, v126, v160
	v_cvt_pk_bf16_f32 v67, v127, v161
	v_cvt_pk_bf16_f32 v68, v158, v162
	v_cvt_pk_bf16_f32 v69, v159, v163
	s_nop 1
	v_permlane32_swap_b32_e32 v64, v65
	v_permlane32_swap_b32_e32 v66, v68
	v_permlane32_swap_b32_e32 v67, v69
	v_cvt_pk_bf16_f32 v70, v118, v121
	v_cvt_pk_bf16_f32 v71, v119, v122
	v_cvt_pk_bf16_f32 v72, v120, v123
	v_cvt_pk_bf16_f32 v73, v124, v125
	v_cvt_pk_bf16_f32 v74, v74, v75
	v_cvt_pk_bf16_f32 v75, v76, v77
	v_cvt_pk_bf16_f32 v76, v78, v79
	v_cvt_pk_bf16_f32 v77, v80, v81
	v_cvt_pk_bf16_f32 v78, v82, v83
	v_cvt_pk_bf16_f32 v79, v84, v85
	v_cvt_pk_bf16_f32 v80, v86, v87
	v_cvt_pk_bf16_f32 v81, v88, v89
	s_nop 0
	v_permlane32_swap_b32_e32 v70, v72
	v_permlane32_swap_b32_e32 v71, v73
	v_permlane32_swap_b32_e32 v74, v76
	v_permlane32_swap_b32_e32 v75, v77
	v_permlane32_swap_b32_e32 v78, v80
	v_permlane32_swap_b32_e32 v79, v81
	ds_read_b64_tr_b16 v[82:83], v144 offset:0
	ds_read_b64_tr_b16 v[84:85], v144 offset:0x800
	ds_read_b64_tr_b16 v[86:87], v144 offset:0x1000
	ds_read_b64_tr_b16 v[88:89], v144 offset:0x1800
	ds_read_b64_tr_b16 v[90:91], v144 offset:0x2000
	ds_read_b64_tr_b16 v[92:93], v144 offset:0x2800
	ds_read_b64_tr_b16 v[94:95], v144 offset:0x3000
	ds_read_b64_tr_b16 v[96:97], v144 offset:0x3800
	s_waitcnt lgkmcnt(0)
; #define SBAR() __builtin_amdgcn_sched_barrier(0)
; #define RESC(a) do { if (__any((a) < 1.f)) { if (hi == 0) al_l[r32] = (a); asm volatile("s_waitcnt lgkmcnt(0)" ::: "memory"); \
;     _Pragma("unroll") for (int d = 0; d < 2; ++d) _Pragma("unroll") for (int r = 0; r < 16; ++r) o[d][r] *= al_l[crow(r, hi)]; } } while (0)
; #define BIAS(P0, P1, j) do { if (MODE == 1) { SBAR(); if ((j) >= nA) na_bias(P0, P1, na, rs0 + (j) - nA, hi); SBAR(); } } while (0)
; template <int DQK, int MODE, int ldq, int ldk, int ldv> ...
;     ...
;   SBAR(); qkt<DQK>(pB0, pB1, K_lds + SHM_K, qr, r32, hi);
;   finishSM(pA0, pA1, alA, l_reg, pa0, pa1, pa2, pa3); SBAR();
;   pv_d0(o, vb0, pa0, pa1, pa2, pa3); BIAS(pB0, pB1, NT - 1); partialSM<DQK>(pB0, pB1, m_reg, mnB, alB);
;   __syncthreads(); RESC(alB);
	s_nop 0
	v_mfma_f32_32x32x16_bf16 v[0:15], v[66:69], v[82:85], v[0:15]
	ds_read_b64_tr_b16 v[82:83], v144 offset:0x200
	ds_read_b64_tr_b16 v[84:85], v144 offset:0xa00
	v_mfma_f32_32x32x16_bf16 v[0:15], v[70:73], v[86:89], v[0:15]
	ds_read_b64_tr_b16 v[86:87], v144 offset:0x1200
	ds_read_b64_tr_b16 v[88:89], v144 offset:0x1a00
	v_mfma_f32_32x32x16_bf16 v[0:15], v[74:77], v[90:93], v[0:15]
	ds_read_b64_tr_b16 v[90:91], v144 offset:0x2200
	ds_read_b64_tr_b16 v[92:93], v144 offset:0x2a00
	v_mfma_f32_32x32x16_bf16 v[0:15], v[78:81], v[94:97], v[0:15]
	ds_read_b64_tr_b16 v[94:95], v144 offset:0x3200
	ds_read_b64_tr_b16 v[96:97], v144 offset:0x3a00
	s_waitcnt lgkmcnt(0)
	v_mfma_f32_32x32x16_bf16 v[16:31], v[66:69], v[82:85], v[16:31]
	v_max_f32_e32 v66, v49, v49
	v_max_f32_e32 v67, v48, v48
	v_max_f32_e32 v66, v67, v66
	v_max3_f32 v66, v66, v50, v51
	v_max3_f32 v66, v66, v52, v53
	v_max3_f32 v66, v66, v54, v55
	v_max3_f32 v66, v66, v56, v57
	v_max3_f32 v66, v66, v58, v59
	v_max3_f32 v66, v66, v60, v61
	v_mfma_f32_32x32x16_bf16 v[16:31], v[70:73], v[86:89], v[16:31]
	v_max3_f32 v66, v66, v62, v63
	v_max3_f32 v66, v66, v32, v33
	v_max3_f32 v66, v66, v34, v35
	v_max3_f32 v66, v66, v36, v37
	v_max3_f32 v66, v66, v38, v39
	v_max3_f32 v66, v66, v40, v41
	v_max3_f32 v66, v66, v42, v43
	v_max3_f32 v66, v66, v44, v45
	v_mfma_f32_32x32x16_bf16 v[16:31], v[74:77], v[90:93], v[16:31]
	v_max3_f32 v66, v66, v46, v47
	v_mov_b32_e32 v67, v66
	s_nop 1
	v_permlane32_swap_b32_e32 v66, v67
	v_max_f32_e32 v67, v67, v67
	v_max_f32_e32 v66, v66, v66
	v_max_f32_e32 v66, v66, v67
	v_sub_f32_e32 v67, v66, v116
	v_cmp_ge_f32_e32 vcc, s80, v67
	v_max_f32_e32 v67, v116, v116
	v_max_f32_e32 v67, v67, v66
	v_mfma_f32_32x32x16_bf16 v[16:31], v[78:81], v[94:97], v[16:31]
	v_sub_f32_e32 v66, v116, v67
	v_mul_f32_e32 v66, 0x3f800000, v66
	v_exp_f32_e32 v66, v66
	s_cmp_eq_u64 vcc, exec
	s_cselect_b64 s[0:1], -1, 0
	v_cndmask_b32_e64 v66, v66, 1.0, s[0:1]
	v_cmp_gt_f32_e32 vcc, 1.0, v66
	s_barrier
	s_cbranch_vccz .LBB0_316
	s_and_saveexec_b64 s[10:11], s[4:5]
	ds_write_b32 v141, v66 offset:128
	s_or_b64 exec, exec, s[10:11]
	s_waitcnt lgkmcnt(0)
	ds_read_b128 v[68:71], v129 offset:224
	ds_read_b128 v[72:75], v129 offset:192
	ds_read_b128 v[76:79], v129 offset:160
	ds_read_b128 v[80:83], v129 offset:128
	s_waitcnt lgkmcnt(3)
	v_pk_mul_f32 v[14:15], v[14:15], v[70:71]
	s_waitcnt lgkmcnt(2)
	v_pk_mul_f32 v[10:11], v[10:11], v[74:75]
	s_waitcnt lgkmcnt(1)
	v_pk_mul_f32 v[6:7], v[6:7], v[78:79]
	s_waitcnt lgkmcnt(0)
	v_pk_mul_f32 v[2:3], v[2:3], v[82:83]
	v_pk_mul_f32 v[12:13], v[12:13], v[68:69]
	v_pk_mul_f32 v[8:9], v[8:9], v[72:73]
	v_pk_mul_f32 v[4:5], v[4:5], v[76:77]
	v_pk_mul_f32 v[0:1], v[0:1], v[80:81]
	v_pk_mul_f32 v[30:31], v[30:31], v[70:71]
	v_pk_mul_f32 v[26:27], v[26:27], v[74:75]
	v_pk_mul_f32 v[22:23], v[22:23], v[78:79]
	v_pk_mul_f32 v[18:19], v[18:19], v[82:83]
	v_pk_mul_f32 v[28:29], v[28:29], v[68:69]
	v_pk_mul_f32 v[24:25], v[24:25], v[72:73]
	v_pk_mul_f32 v[20:21], v[20:21], v[76:77]
	v_pk_mul_f32 v[16:17], v[16:17], v[80:81]
; #define SBAR() __builtin_amdgcn_sched_barrier(0)
; #define RESC(a) do { if (__any((a) < 1.f)) { if (hi == 0) al_l[r32] = (a); asm volatile("s_waitcnt lgkmcnt(0)" ::: "memory"); \
;     _Pragma("unroll") for (int d = 0; d < 2; ++d) _Pragma("unroll") for (int r = 0; r < 16; ++r) o[d][r] *= al_l[crow(r, hi)]; } } while (0)
; template <int DQK, int MODE, int ldq, int ldk, int ldv> ...
;     ...
;   __syncthreads(); RESC(alB);
;   finishSM(pB0, pB1, alB, l_reg, pa0, pa1, pa2, pa3); SBAR();
;   pv_d0(o, vb0 + (int)SHM_V, pa0, pa1, pa2, pa3);
;   if (hi == 0) li_l[r32] = l_reg; asm volatile("s_waitcnt lgkmcnt(0)" ::: "memory");
.LBB0_316:
	v_cndmask_b32_e64 v67, v67, v116, s[0:1]
	v_mul_f32_e32 v67, 0xbf800000, v67
	v_fmamk_f32 v48, v48, 0x3f800000, v67
	v_fmamk_f32 v49, v49, 0x3f800000, v67
	v_fmamk_f32 v68, v50, 0x3f800000, v67
	v_exp_f32_e32 v50, v48
	v_fmamk_f32 v69, v52, 0x3f800000, v67
	v_exp_f32_e32 v52, v49
	v_fmamk_f32 v51, v51, 0x3f800000, v67
	v_exp_f32_e32 v48, v68
	v_fmamk_f32 v32, v32, 0x3f800000, v67
	v_exp_f32_e32 v51, v51
	v_fmamk_f32 v70, v53, 0x3f800000, v67
	v_fmamk_f32 v79, v62, 0x3f800000, v67
	v_fmamk_f32 v62, v43, 0x3f800000, v67
	v_exp_f32_e32 v43, v69
	v_exp_f32_e32 v68, v32
	v_add_f32_e32 v32, 0, v50
	v_fmamk_f32 v71, v54, 0x3f800000, v67
	v_exp_f32_e32 v49, v70
	v_add_f32_e32 v32, v52, v32
	v_fmamk_f32 v72, v55, 0x3f800000, v67
	v_fmamk_f32 v78, v61, 0x3f800000, v67
	v_fmamk_f32 v61, v42, 0x3f800000, v67
	v_exp_f32_e32 v42, v71
	v_add_f32_e32 v32, v48, v32
	v_fmamk_f32 v73, v56, 0x3f800000, v67
	v_fmamk_f32 v80, v63, 0x3f800000, v67
	v_fmamk_f32 v63, v44, 0x3f800000, v67
	v_exp_f32_e32 v44, v72
	v_add_f32_e32 v32, v51, v32
	v_fmamk_f32 v74, v57, 0x3f800000, v67
	v_fmamk_f32 v75, v58, 0x3f800000, v67
	v_fmamk_f32 v58, v39, 0x3f800000, v67
	v_exp_f32_e32 v39, v73
	v_add_f32_e32 v32, v43, v32
	v_fmamk_f32 v77, v60, 0x3f800000, v67
	v_fmamk_f32 v60, v41, 0x3f800000, v67
	v_exp_f32_e32 v41, v74
	v_add_f32_e32 v32, v49, v32
	v_fmamk_f32 v76, v59, 0x3f800000, v67
	v_fmamk_f32 v56, v37, 0x3f800000, v67
	v_exp_f32_e32 v37, v75
	v_add_f32_e32 v32, v42, v32
	v_fmamk_f32 v59, v40, 0x3f800000, v67
	v_exp_f32_e32 v40, v76
	v_add_f32_e32 v32, v44, v32
	v_fmamk_f32 v54, v35, 0x3f800000, v67
	v_exp_f32_e32 v35, v77
	v_add_f32_e32 v32, v39, v32
	v_fmamk_f32 v57, v38, 0x3f800000, v67
	v_exp_f32_e32 v38, v78
	v_add_f32_e32 v32, v41, v32
	v_fmamk_f32 v53, v34, 0x3f800000, v67
	v_exp_f32_e32 v34, v79
	v_add_f32_e32 v32, v37, v32
	v_fmamk_f32 v55, v36, 0x3f800000, v67
	v_exp_f32_e32 v36, v80
	v_add_f32_e32 v32, v40, v32
	v_fmamk_f32 v33, v33, 0x3f800000, v67
	v_add_f32_e32 v32, v35, v32
	v_exp_f32_e32 v69, v33
	v_add_f32_e32 v32, v38, v32
	v_exp_f32_e32 v53, v53
	v_add_f32_e32 v32, v34, v32
	v_exp_f32_e32 v54, v54
	v_add_f32_e32 v32, v36, v32
	v_exp_f32_e32 v55, v55
	v_add_f32_e32 v32, v68, v32
	v_exp_f32_e32 v56, v56
	v_add_f32_e32 v32, v69, v32
	v_exp_f32_e32 v57, v57
	v_add_f32_e32 v32, v53, v32
	v_exp_f32_e32 v58, v58
	v_add_f32_e32 v32, v54, v32
	v_exp_f32_e32 v59, v59
	v_add_f32_e32 v32, v55, v32
	v_exp_f32_e32 v60, v60
	v_add_f32_e32 v32, v56, v32
	v_exp_f32_e32 v61, v61
	v_add_f32_e32 v32, v57, v32
	v_exp_f32_e32 v62, v62
	v_add_f32_e32 v32, v58, v32
	v_fmamk_f32 v45, v45, 0x3f800000, v67
	v_exp_f32_e32 v63, v63
	v_add_f32_e32 v32, v59, v32
	v_fmamk_f32 v46, v46, 0x3f800000, v67
	v_exp_f32_e32 v70, v45
	v_add_f32_e32 v32, v60, v32
	v_fmac_f32_e32 v67, 0x3f800000, v47
	v_exp_f32_e32 v71, v46
	v_add_f32_e32 v32, v61, v32
	v_exp_f32_e32 v67, v67
	v_add_f32_e32 v32, v62, v32
	v_add_f32_e32 v32, v63, v32
	v_add_f32_e32 v32, v70, v32
	v_add_f32_e32 v32, v71, v32
	v_add_f32_e32 v32, v67, v32
	v_mov_b32_e32 v33, v32
	s_nop 1
	v_permlane32_swap_b32_e32 v32, v33
	v_cvt_pk_bf16_f32 v46, v50, v52
	v_cvt_pk_bf16_f32 v47, v48, v51
	v_cvt_pk_bf16_f32 v48, v43, v49
	v_cvt_pk_bf16_f32 v49, v42, v44
	v_cvt_pk_bf16_f32 v42, v39, v41
	v_cvt_pk_bf16_f32 v43, v37, v40
	v_cvt_pk_bf16_f32 v44, v35, v38
	v_cvt_pk_bf16_f32 v45, v34, v36
	v_cvt_pk_bf16_f32 v34, v68, v69
	v_cvt_pk_bf16_f32 v35, v53, v54
	v_cvt_pk_bf16_f32 v36, v55, v56
	v_cvt_pk_bf16_f32 v37, v57, v58
	v_cvt_pk_bf16_f32 v38, v59, v60
	v_cvt_pk_bf16_f32 v39, v61, v62
	v_cvt_pk_bf16_f32 v40, v63, v70
	v_cvt_pk_bf16_f32 v41, v71, v67
	s_nop 0
	v_permlane32_swap_b32_e32 v46, v48
	v_permlane32_swap_b32_e32 v47, v49
	v_permlane32_swap_b32_e32 v42, v44
	v_permlane32_swap_b32_e32 v43, v45
	v_permlane32_swap_b32_e32 v34, v36
	v_permlane32_swap_b32_e32 v35, v37
	v_permlane32_swap_b32_e32 v38, v40
	v_permlane32_swap_b32_e32 v39, v41
	ds_read_b64_tr_b16 v[50:51], v143 offset:0
	ds_read_b64_tr_b16 v[52:53], v143 offset:0x800
	ds_read_b64_tr_b16 v[54:55], v143 offset:0x1000
	ds_read_b64_tr_b16 v[56:57], v143 offset:0x1800
	ds_read_b64_tr_b16 v[58:59], v143 offset:0x2000
	ds_read_b64_tr_b16 v[60:61], v143 offset:0x2800
	ds_read_b64_tr_b16 v[68:69], v143 offset:0x3000
	ds_read_b64_tr_b16 v[70:71], v143 offset:0x3800
	s_waitcnt lgkmcnt(0)
	s_nop 0
	v_mfma_f32_32x32x16_bf16 v[0:15], v[46:49], v[50:53], v[0:15]
	ds_read_b64_tr_b16 v[50:51], v143 offset:0x200
	ds_read_b64_tr_b16 v[52:53], v143 offset:0xa00
	v_mfma_f32_32x32x16_bf16 v[0:15], v[42:45], v[54:57], v[0:15]
	ds_read_b64_tr_b16 v[54:55], v143 offset:0x1200
	ds_read_b64_tr_b16 v[56:57], v143 offset:0x1a00
	v_mfma_f32_32x32x16_bf16 v[0:15], v[34:37], v[58:61], v[0:15]
	ds_read_b64_tr_b16 v[58:59], v143 offset:0x2200
	ds_read_b64_tr_b16 v[60:61], v143 offset:0x2a00
	v_mfma_f32_32x32x16_bf16 v[0:15], v[38:41], v[68:71], v[0:15]
	ds_read_b64_tr_b16 v[68:69], v143 offset:0x3200
	ds_read_b64_tr_b16 v[70:71], v143 offset:0x3a00
	s_waitcnt lgkmcnt(0)
	v_mfma_f32_32x32x16_bf16 v[16:31], v[46:49], v[50:53], v[16:31]
	v_mfma_f32_32x32x16_bf16 v[16:31], v[42:45], v[54:57], v[16:31]
	v_mfma_f32_32x32x16_bf16 v[16:31], v[34:37], v[58:61], v[16:31]
	v_mfma_f32_32x32x16_bf16 v[16:31], v[38:41], v[68:71], v[16:31]
	s_and_saveexec_b64 s[0:1], s[4:5]
	s_cbranch_execz .LBB0_298
	v_add_f32_e32 v34, v64, v65
	v_fmac_f32_e32 v34, v142, v117
	v_add_f32_e32 v32, v32, v33
	v_fmac_f32_e32 v32, v34, v66
	ds_write_b32 v141, v32
	s_branch .LBB0_298
